# hand-written cross attention: LDS-DMA K/V stages with source-side XOR swizzle, L2 warm-up of the next stages, plus H2 rewrite and GEMM unit-start wait removal
# speedup vs baseline: 1.0051x; 1.0051x over previous
; #define LAS __attribute__((address_space(3)))
; #define DSEC(k) do { if (PROBE_DSEC) { const unsigned long long tn_ = __builtin_amdgcn_s_memrealtime(); if (PROBE_DSEC == (k)) tsec += tn_ - tl_; tl_ = tn_; } } while (0)
; #define XK_LOAD(R, b_, h_, hh_) do { _Pragma("unroll") for (int i = 0; i < 8; ++i) { const int p = tid + 512 * i, m = p >> 4, cb = p & 15; R[i] = *(const u32x4*)(memK + (size_t)((b_) * NMEM + m) * D + (h_) * 256 + 128 * (hh_) + 8 * cb); } } while (0)
; #define XK_WRITE(R) do { _Pragma("unroll") for (int i = 0; i < 8; ++i) { const int p = tid + 512 * i, m = p >> 4, cb = p & 15; *(LAS u32x4*)(KL + m * KSTR + 16 * cb) = R[i]; } } while (0)
; DI void xattn_phase(LAS unsigned char* L, const bf16* Qx, const bf16* memK, const bf16* memVT, bf16* Ox, int G, int bid, int tid, unsigned long long& tsec) {
;     unsigned long long tl_ = PROBE_DSEC ? __builtin_amdgcn_s_memrealtime() : 0;
;     const int wid = __builtin_amdgcn_readfirstlane(tid >> 6), lane = tid & 63, fr = lane & 15, fq = lane >> 4;
;     LAS unsigned char* KL = L; LAS unsigned char* VL = L + KL_BYTES;
;     u32x4 ra[8], rb[8];
;     if (bid < 512) { const int h0 = (bid >> 5) & 3, b0 = bid >> 7; XK_LOAD(ra, b0, h0, 0); XV_LOAD(rb, b0, h0, 0); }
;     for (int unit = bid; unit < 512; unit += G) {
;         const int j = unit & 31, h = (unit >> 5) & 3, b = unit >> 7;
;         const int nun = unit + G < 512 ? unit + G : unit, hn = (nun >> 5) & 3, bn = nun >> 7;
;         asm volatile("" : "+v"(ra[0]), "+v"(ra[1]), "+v"(ra[2]), "+v"(ra[3]), "+v"(ra[4]), "+v"(ra[5]), "+v"(ra[6]), "+v"(ra[7]));
;         asm volatile("" : "+v"(rb[0]), "+v"(rb[1]), "+v"(rb[2]), "+v"(rb[3]), "+v"(rb[4]), "+v"(rb[5]), "+v"(rb[6]), "+v"(rb[7]));
;         const int tok0 = b * T + 128 * j; const size_t tq = (size_t)(tok0 + 16 * wid + fr);
;         f32x4 s[16];
; #pragma unroll
;         for (int kt = 0; kt < 16; ++kt) s[kt] = (f32x4){0.f, 0.f, 0.f, 0.f};
; #pragma unroll
;         for (int hh = 0; hh < 2; ++hh) {
;             __syncthreads();
;             XK_WRITE(ra);
;             if (hh == 0) { XV_WRITE(rb); XK_LOAD(ra, b, h, 1); XV_LOAD(rb, b, h, 1); }
;             else XK_LOAD(ra, bn, hn, 0);
;             __syncthreads();
;             DSEC(11);
; #pragma unroll
;             for (int k4 = 0; k4 < 4; ++k4) { const bf16x8 qk = *(const bf16x8*)(Qx + tq * D + h * 256 + 128 * hh + 32 * k4 + 8 * fq);
.LBB0_1099:
	s_cmpk_gt_i32 s4, 0x1ff
	v_readfirstlane_b32 s5, v67
	s_cbranch_scc1 .LBB0_1102
	v_readlane_b32 s2, v254, 29
	v_readlane_b32 s3, v254, 30
	s_and_b64 s[2:3], s[2:3], exec
	s_brev_b32 s2, 40
	s_mov_b32 s3, 0x14200000
	s_cselect_b32 s2, s2, 0x14c00000
	s_cselect_b32 s3, s3, 0x14e00000
	s_add_u32 s6, s78, s0
	s_addc_u32 s7, s79, s1
	s_add_u32 s0, s6, 0x6400000
	s_addc_u32 s1, s7, 0
	s_add_u32 s36, s6, s2
	s_addc_u32 s37, s7, 0
	s_add_u32 s2, s6, s3
	s_addc_u32 s3, s7, 0
	s_add_u32 s38, s6, 0x8400000
	s_addc_u32 s39, s7, 0
	s_lshr_b32 s16, s5, 6
	s_lshl_b32 s49, s16, 13
	s_mov_b32 s48, 0x3d800000
	v_and_b32_e32 v236, 63, v67
	v_and_b32_e32 v237, 15, v236
	v_lshrrev_b32_e32 v248, 4, v236
	v_xor_b32_e32 v234, 16, v236
	v_lshlrev_b32_e32 v234, 2, v234
	v_xor_b32_e32 v235, 32, v236
	v_lshlrev_b32_e32 v235, 2, v235
	v_add_u32_e32 v249, 0, v248
	v_xor_b32_e32 v198, v237, v249
	v_lshl_add_u32 v249, s16, 5, v249
	v_lshlrev_b32_e32 v249, 11, v249
	v_lshl_add_u32 v198, v198, 4, v249
	v_add_u32_e32 v249, 4, v248
	v_xor_b32_e32 v199, v237, v249
	v_lshl_add_u32 v249, s16, 5, v249
	v_lshlrev_b32_e32 v249, 11, v249
	v_lshl_add_u32 v199, v199, 4, v249
	v_add_u32_e32 v249, 8, v248
	v_xor_b32_e32 v200, v237, v249
	v_lshl_add_u32 v249, s16, 5, v249
	v_lshlrev_b32_e32 v249, 11, v249
	v_lshl_add_u32 v200, v200, 4, v249
	v_add_u32_e32 v249, 12, v248
	v_xor_b32_e32 v201, v237, v249
	v_lshl_add_u32 v249, s16, 5, v249
	v_lshlrev_b32_e32 v249, 11, v249
	v_lshl_add_u32 v201, v201, 4, v249
	v_add_u32_e32 v249, 0, v248
	v_xor_b32_e32 v249, v249, v237
	v_lshlrev_b32_e32 v249, 4, v249
	v_lshl_add_u32 v206, v237, 8, v249
	v_add_u32_e32 v212, 0x10000, v206
	v_add_u32_e32 v249, 4, v248
	v_xor_b32_e32 v249, v249, v237
	v_lshlrev_b32_e32 v249, 4, v249
	v_lshl_add_u32 v207, v237, 8, v249
	v_add_u32_e32 v213, 0x10000, v207
	v_add_u32_e32 v249, 8, v248
	v_xor_b32_e32 v249, v249, v237
	v_lshlrev_b32_e32 v249, 4, v249
	v_lshl_add_u32 v208, v237, 8, v249
	v_add_u32_e32 v214, 0x10000, v208
	v_add_u32_e32 v249, 12, v248
	v_xor_b32_e32 v249, v249, v237
	v_lshlrev_b32_e32 v249, 4, v249
	v_lshl_add_u32 v209, v237, 8, v249
	v_add_u32_e32 v215, 0x10000, v209
	v_lshrrev_b32_e32 v0, 1, v248
	v_add_u32_e32 v249, 0, v0
	v_xor_b32_e32 v249, v249, v237
	v_lshlrev_b32_e32 v249, 4, v249
	v_lshl_add_u32 v216, v237, 9, v249
	v_add_u32_e32 v249, 2, v0
	v_xor_b32_e32 v249, v249, v237
	v_lshlrev_b32_e32 v249, 4, v249
	v_lshl_add_u32 v217, v237, 9, v249
	v_add_u32_e32 v249, 4, v0
	v_xor_b32_e32 v249, v249, v237
	v_lshlrev_b32_e32 v249, 4, v249
	v_lshl_add_u32 v218, v237, 9, v249
	v_add_u32_e32 v249, 6, v0
	v_xor_b32_e32 v249, v249, v237
	v_lshlrev_b32_e32 v249, 4, v249
	v_lshl_add_u32 v219, v237, 9, v249
	v_add_u32_e32 v249, 8, v0
	v_xor_b32_e32 v249, v249, v237
	v_lshlrev_b32_e32 v249, 4, v249
	v_lshl_add_u32 v220, v237, 9, v249
	v_add_u32_e32 v249, 10, v0
	v_xor_b32_e32 v249, v249, v237
	v_lshlrev_b32_e32 v249, 4, v249
	v_lshl_add_u32 v221, v237, 9, v249
	v_add_u32_e32 v249, 12, v0
	v_xor_b32_e32 v249, v249, v237
	v_lshlrev_b32_e32 v249, 4, v249
	v_lshl_add_u32 v222, v237, 9, v249
	v_add_u32_e32 v249, 14, v0
	v_xor_b32_e32 v249, v249, v237
	v_lshlrev_b32_e32 v249, 4, v249
	v_lshl_add_u32 v223, v237, 9, v249
	v_and_b32_e32 v249, 1, v248
	v_lshlrev_b32_e32 v249, 3, v249
	v_add_u32_e32 v216, v216, v249
	v_add_u32_e32 v224, 0x10000, v216
	v_add_u32_e32 v217, v217, v249
	v_add_u32_e32 v225, 0x10000, v217
	v_add_u32_e32 v218, v218, v249
	v_add_u32_e32 v226, 0x10000, v218
	v_add_u32_e32 v219, v219, v249
	v_add_u32_e32 v227, 0x10000, v219
	v_add_u32_e32 v220, v220, v249
	v_add_u32_e32 v228, 0x10000, v220
	v_add_u32_e32 v221, v221, v249
	v_add_u32_e32 v229, 0x10000, v221
	v_add_u32_e32 v222, v222, v249
	v_add_u32_e32 v230, 0x10000, v222
	v_add_u32_e32 v223, v223, v249
	v_add_u32_e32 v231, 0x10000, v223
	v_lshl_add_u32 v249, s16, 4, v237
	v_lshlrev_b32_e32 v249, 11, v249
	v_lshl_add_u32 v232, v248, 4, v249
	v_lshl_add_u32 v233, v248, 3, v249
	s_mov_b32 s17, s4
	s_and_b32 s44, s17, 31
	s_bfe_u32 s45, s17, 0x20005
	s_lshr_b32 s46, s17, 7
	s_lshl_b32 s47, s46, 12
	s_lshl_b32 s44, s44, 7
	s_add_u32 s47, s47, s44
	s_lshl_b32 s47, s47, 11
	s_lshl_b32 s44, s45, 9
	s_add_u32 s47, s47, s44
	s_add_u32 s20, s0, s47
	s_addc_u32 s21, s1, 0
	s_add_u32 s22, s38, s47
	s_addc_u32 s23, s39, 0
	s_lshl_b32 s47, s46, 19
	s_add_u32 s47, s47, s44
	s_add_u32 s24, s36, s47
	s_addc_u32 s25, s37, 0
	s_lshl_b32 s47, s45, 19
	s_lshl_b32 s44, s46, 9
	s_add_u32 s47, s47, s44
	s_add_u32 s42, s2, s47
	s_addc_u32 s43, s3, 0
	s_add_u32 s44, s24, 0
	s_addc_u32 s45, s25, 0
	s_add_u32 s46, s44, 0x8000
	s_addc_u32 s47, s45, 0
	s_add_u32 m0, s49, 0
	s_nop 0
	global_load_lds_dwordx4 v198, s[44:45]
	s_add_u32 m0, s49, 1024
	s_nop 0
	global_load_lds_dwordx4 v199, s[44:45]
	s_add_u32 m0, s49, 2048
	s_nop 0
	global_load_lds_dwordx4 v200, s[44:45]
	s_add_u32 m0, s49, 3072
	s_nop 0
	global_load_lds_dwordx4 v201, s[44:45]
	s_add_u32 m0, s49, 4096
	s_nop 0
	global_load_lds_dwordx4 v198, s[46:47]
	s_add_u32 m0, s49, 5120
	s_nop 0
	global_load_lds_dwordx4 v199, s[46:47]
	s_add_u32 m0, s49, 6144
	s_nop 0
	global_load_lds_dwordx4 v200, s[46:47]
	s_add_u32 m0, s49, 7168
	s_nop 0
	global_load_lds_dwordx4 v201, s[46:47]
	global_load_dwordx4 v[66:69], v232, s[20:21]
	global_load_dwordx4 v[70:73], v232, s[20:21] offset:64
	global_load_dwordx4 v[74:77], v232, s[20:21] offset:128
	global_load_dwordx4 v[78:81], v232, s[20:21] offset:192
	global_load_dwordx4 v[82:85], v232, s[20:21] offset:256
	global_load_dwordx4 v[86:89], v232, s[20:21] offset:320
	global_load_dwordx4 v[90:93], v232, s[20:21] offset:384
	global_load_dwordx4 v[94:97], v232, s[20:21] offset:448
; #define LAS __attribute__((address_space(3)))
; #define MFMA16(a, b, c) __builtin_amdgcn_mfma_f32_16x16x32_bf16((a), (b), (c), 0, 0, 0)
; DI void xattn_phase(LAS unsigned char* L, const bf16* Qx, const bf16* memK, const bf16* memVT, bf16* Ox, int G, int bid, int tid, unsigned long long& tsec) {
;     unsigned long long tl_ = PROBE_DSEC ? __builtin_amdgcn_s_memrealtime() : 0;
;     const int wid = __builtin_amdgcn_readfirstlane(tid >> 6), lane = tid & 63, fr = lane & 15, fq = lane >> 4;
;     LAS unsigned char* KL = L; LAS unsigned char* VL = L + KL_BYTES;
;     u32x4 ra[8], rb[8];
;     if (bid < 512) { const int h0 = (bid >> 5) & 3, b0 = bid >> 7; XK_LOAD(ra, b0, h0, 0); XV_LOAD(rb, b0, h0, 0); }
;     for (int unit = bid; unit < 512; unit += G) {
;         const int j = unit & 31, h = (unit >> 5) & 3, b = unit >> 7;
;         const int nun = unit + G < 512 ? unit + G : unit, hn = (nun >> 5) & 3, bn = nun >> 7;
;         asm volatile("" : "+v"(ra[0]), "+v"(ra[1]), "+v"(ra[2]), "+v"(ra[3]), "+v"(ra[4]), "+v"(ra[5]), "+v"(ra[6]), "+v"(ra[7]));
;         asm volatile("" : "+v"(rb[0]), "+v"(rb[1]), "+v"(rb[2]), "+v"(rb[3]), "+v"(rb[4]), "+v"(rb[5]), "+v"(rb[6]), "+v"(rb[7]));
;         const int tok0 = b * T + 128 * j; const size_t tq = (size_t)(tok0 + 16 * wid + fr);
;         f32x4 s[16];
; #pragma unroll
;         for (int kt = 0; kt < 16; ++kt) s[kt] = (f32x4){0.f, 0.f, 0.f, 0.f};
; #pragma unroll
;         for (int hh = 0; hh < 2; ++hh) {
;             __syncthreads();
;             XK_WRITE(ra);
;             if (hh == 0) { XV_WRITE(rb); XK_LOAD(ra, b, h, 1); XV_LOAD(rb, b, h, 1); }
;             else XK_LOAD(ra, bn, hn, 0);
;             __syncthreads();
;             DSEC(11);
; #pragma unroll
;             for (int k4 = 0; k4 < 4; ++k4) { const bf16x8 qk = *(const bf16x8*)(Qx + tq * D + h * 256 + 128 * hh + 32 * k4 + 8 * fq);
; #pragma unroll
;                 for (int k8 = 0; k8 < 4; ++k8) { bf16x8 av[4];
; #pragma unroll
;                     for (int kt = 0; kt < 4; ++kt) av[kt] = *(const LAS bf16x8*)(KL + (16 * (4 * k8 + kt) + fr) * KSTR + (32 * k4 + 8 * fq) * 2);
; #pragma unroll
;                     for (int kt = 0; kt < 4; ++kt) s[4 * k8 + kt] = MFMA16(av[kt], qk, s[4 * k8 + kt]); } }
	s_lshl_b32 s46, s16, 1
	s_add_u32 s46, s46, 0
	v_lshl_add_u32 v237, s46, 6, v236
	v_lshrrev_b32_e32 v248, 2, v237
	v_and_b32_e32 v237, 3, v237
	v_lshlrev_b32_e32 v237, 6, v237
	v_lshl_add_u32 v237, v248, 11, v237
	global_load_dword v249, v237, s[24:25] offset:256
	s_lshl_b32 s46, s16, 1
	s_add_u32 s46, s46, 1
	v_lshl_add_u32 v237, s46, 6, v236
	v_lshrrev_b32_e32 v248, 2, v237
	v_and_b32_e32 v237, 3, v237
	v_lshlrev_b32_e32 v237, 6, v237
	v_lshl_add_u32 v237, v248, 11, v237
	global_load_dword v249, v237, s[24:25] offset:256
	s_lshl_b32 s46, s16, 2
	s_add_u32 s46, s46, 0
	v_lshl_add_u32 v237, s46, 6, v236
	v_lshrrev_b32_e32 v248, 3, v237
	v_and_b32_e32 v237, 7, v237
	v_lshlrev_b32_e32 v237, 6, v237
	v_lshl_add_u32 v237, v248, 11, v237
	global_load_dword v249, v237, s[42:43]
	s_lshl_b32 s46, s16, 2
	s_add_u32 s46, s46, 1
	v_lshl_add_u32 v237, s46, 6, v236
	v_lshrrev_b32_e32 v248, 3, v237
	v_and_b32_e32 v237, 7, v237
	v_lshlrev_b32_e32 v237, 6, v237
	v_lshl_add_u32 v237, v248, 11, v237
	global_load_dword v249, v237, s[42:43]
	s_lshl_b32 s46, s16, 2
	s_add_u32 s46, s46, 2
	v_lshl_add_u32 v237, s46, 6, v236
	v_lshrrev_b32_e32 v248, 3, v237
	v_and_b32_e32 v237, 7, v237
	v_lshlrev_b32_e32 v237, 6, v237
	v_lshl_add_u32 v237, v248, 11, v237
	global_load_dword v249, v237, s[42:43]
	s_lshl_b32 s46, s16, 2
	s_add_u32 s46, s46, 3
	v_lshl_add_u32 v237, s46, 6, v236
	v_lshrrev_b32_e32 v248, 3, v237
	v_and_b32_e32 v237, 7, v237
	v_lshlrev_b32_e32 v237, 6, v237
	v_lshl_add_u32 v237, v248, 11, v237
	global_load_dword v249, v237, s[42:43]
	s_waitcnt vmcnt(0)
	s_barrier
.Lxa_loop:
	s_add_u32 s44, s24, 256
	s_addc_u32 s45, s25, 0
	s_add_u32 s46, s44, 0x8000
	s_addc_u32 s47, s45, 0
	s_add_u32 m0, s49, 65536
	s_nop 0
	global_load_lds_dwordx4 v198, s[44:45]
	s_add_u32 m0, s49, 66560
	s_nop 0
	global_load_lds_dwordx4 v199, s[44:45]
	s_add_u32 m0, s49, 67584
	s_nop 0
	global_load_lds_dwordx4 v200, s[44:45]
	s_add_u32 m0, s49, 68608
	s_nop 0
	global_load_lds_dwordx4 v201, s[44:45]
	s_add_u32 m0, s49, 69632
	s_nop 0
	global_load_lds_dwordx4 v198, s[46:47]
	s_add_u32 m0, s49, 70656
	s_nop 0
	global_load_lds_dwordx4 v199, s[46:47]
	s_add_u32 m0, s49, 71680
	s_nop 0
	global_load_lds_dwordx4 v200, s[46:47]
	s_add_u32 m0, s49, 72704
	s_nop 0
	global_load_lds_dwordx4 v201, s[46:47]
	ds_read_b128 v[98:101], v206 offset:0
	ds_read_b128 v[102:105], v206 offset:4096
	ds_read_b128 v[106:109], v206 offset:8192
	ds_read_b128 v[110:113], v206 offset:12288
	ds_read_b128 v[114:117], v206 offset:16384
	ds_read_b128 v[118:121], v206 offset:20480
	ds_read_b128 v[122:125], v206 offset:24576
	ds_read_b128 v[126:129], v206 offset:28672
	ds_read_b128 v[130:133], v206 offset:32768
	ds_read_b128 v[134:137], v206 offset:36864
	ds_read_b128 v[138:141], v206 offset:40960
	ds_read_b128 v[142:145], v206 offset:45056
	ds_read_b128 v[146:149], v206 offset:49152
	ds_read_b128 v[150:153], v206 offset:53248
	ds_read_b128 v[154:157], v206 offset:57344
	ds_read_b128 v[158:161], v206 offset:61440
	s_waitcnt lgkmcnt(8)
	v_mfma_f32_16x16x32_bf16 v[2:5], v[98:101], v[66:69], 0
	ds_read_b128 v[98:101], v207 offset:0
	v_mfma_f32_16x16x32_bf16 v[6:9], v[102:105], v[66:69], 0
	ds_read_b128 v[102:105], v207 offset:4096
	v_mfma_f32_16x16x32_bf16 v[10:13], v[106:109], v[66:69], 0
	ds_read_b128 v[106:109], v207 offset:8192
	v_mfma_f32_16x16x32_bf16 v[14:17], v[110:113], v[66:69], 0
	ds_read_b128 v[110:113], v207 offset:12288
	v_mfma_f32_16x16x32_bf16 v[18:21], v[114:117], v[66:69], 0
	ds_read_b128 v[114:117], v207 offset:16384
	v_mfma_f32_16x16x32_bf16 v[22:25], v[118:121], v[66:69], 0
	ds_read_b128 v[118:121], v207 offset:20480
	v_mfma_f32_16x16x32_bf16 v[26:29], v[122:125], v[66:69], 0
	ds_read_b128 v[122:125], v207 offset:24576
	v_mfma_f32_16x16x32_bf16 v[30:33], v[126:129], v[66:69], 0
	ds_read_b128 v[126:129], v207 offset:28672
	s_waitcnt lgkmcnt(8)
	v_mfma_f32_16x16x32_bf16 v[34:37], v[130:133], v[66:69], 0
	ds_read_b128 v[130:133], v207 offset:32768
	v_mfma_f32_16x16x32_bf16 v[38:41], v[134:137], v[66:69], 0
	ds_read_b128 v[134:137], v207 offset:36864
	v_mfma_f32_16x16x32_bf16 v[42:45], v[138:141], v[66:69], 0
	ds_read_b128 v[138:141], v207 offset:40960
	v_mfma_f32_16x16x32_bf16 v[46:49], v[142:145], v[66:69], 0
	ds_read_b128 v[142:145], v207 offset:45056
	v_mfma_f32_16x16x32_bf16 v[50:53], v[146:149], v[66:69], 0
	ds_read_b128 v[146:149], v207 offset:49152
	v_mfma_f32_16x16x32_bf16 v[54:57], v[150:153], v[66:69], 0
	ds_read_b128 v[150:153], v207 offset:53248
	v_mfma_f32_16x16x32_bf16 v[58:61], v[154:157], v[66:69], 0
	ds_read_b128 v[154:157], v207 offset:57344
	v_mfma_f32_16x16x32_bf16 v[62:65], v[158:161], v[66:69], 0
	ds_read_b128 v[158:161], v207 offset:61440
	s_waitcnt lgkmcnt(8)
	v_mfma_f32_16x16x32_bf16 v[2:5], v[98:101], v[70:73], v[2:5]
	ds_read_b128 v[98:101], v208 offset:0
	v_mfma_f32_16x16x32_bf16 v[6:9], v[102:105], v[70:73], v[6:9]
	ds_read_b128 v[102:105], v208 offset:4096
	v_mfma_f32_16x16x32_bf16 v[10:13], v[106:109], v[70:73], v[10:13]
	ds_read_b128 v[106:109], v208 offset:8192
	v_mfma_f32_16x16x32_bf16 v[14:17], v[110:113], v[70:73], v[14:17]
	ds_read_b128 v[110:113], v208 offset:12288
	v_mfma_f32_16x16x32_bf16 v[18:21], v[114:117], v[70:73], v[18:21]
	ds_read_b128 v[114:117], v208 offset:16384
	v_mfma_f32_16x16x32_bf16 v[22:25], v[118:121], v[70:73], v[22:25]
	ds_read_b128 v[118:121], v208 offset:20480
	v_mfma_f32_16x16x32_bf16 v[26:29], v[122:125], v[70:73], v[26:29]
	ds_read_b128 v[122:125], v208 offset:24576
	v_mfma_f32_16x16x32_bf16 v[30:33], v[126:129], v[70:73], v[30:33]
	ds_read_b128 v[126:129], v208 offset:28672
	s_waitcnt lgkmcnt(8)
; #define LAS __attribute__((address_space(3)))
; #define MFMA16(a, b, c) __builtin_amdgcn_mfma_f32_16x16x32_bf16((a), (b), (c), 0, 0, 0)
; #define DSEC(k) do { if (PROBE_DSEC) { const unsigned long long tn_ = __builtin_amdgcn_s_memrealtime(); if (PROBE_DSEC == (k)) tsec += tn_ - tl_; tl_ = tn_; } } while (0)
; #define XK_LOAD(R, b_, h_, hh_) do { _Pragma("unroll") for (int i = 0; i < 8; ++i) { const int p = tid + 512 * i, m = p >> 4, cb = p & 15; R[i] = *(const u32x4*)(memK + (size_t)((b_) * NMEM + m) * D + (h_) * 256 + 128 * (hh_) + 8 * cb); } } while (0)
; #define XK_WRITE(R) do { _Pragma("unroll") for (int i = 0; i < 8; ++i) { const int p = tid + 512 * i, m = p >> 4, cb = p & 15; *(LAS u32x4*)(KL + m * KSTR + 16 * cb) = R[i]; } } while (0)
; #define XV_LOAD(R, b_, h_, hh_) do { _Pragma("unroll") for (int i = 0; i < 8; ++i) { const int p = tid + 512 * i, dhr = p >> 5, c = p & 31; R[i] = *(const u32x4*)(memVT + (size_t)((h_) * 256 + 128 * (hh_) + dhr) * MROWS + (b_) * NMEM + 8 * c); } } while (0)
; #define XV_WRITE(R) do { _Pragma("unroll") for (int i = 0; i < 8; ++i) { const int p = tid + 512 * i, dhr = p >> 5, c = p & 31; u32x2 lo, hi; lo.x = R[i].x; lo.y = R[i].y; hi.x = R[i].z; hi.y = R[i].w; \
;         *(LAS u32x2*)(VL + vt_off(dhr, 2 * c)) = lo; *(LAS u32x2*)(VL + vt_off(dhr, 2 * c + 1)) = hi; } } while (0)
; DI void xattn_phase(LAS unsigned char* L, const bf16* Qx, const bf16* memK, const bf16* memVT, bf16* Ox, int G, int bid, int tid, unsigned long long& tsec) {
;     ...
;         for (int hh = 0; hh < 2; ++hh) {
;             __syncthreads();
;             XK_WRITE(ra);
;             if (hh == 0) { XV_WRITE(rb); XK_LOAD(ra, b, h, 1); XV_LOAD(rb, b, h, 1); }
;             else XK_LOAD(ra, bn, hn, 0);
;             __syncthreads();
;             DSEC(11);
; #pragma unroll
;             for (int k4 = 0; k4 < 4; ++k4) { const bf16x8 qk = *(const bf16x8*)(Qx + tq * D + h * 256 + 128 * hh + 32 * k4 + 8 * fq);
; #pragma unroll
;                 for (int k8 = 0; k8 < 4; ++k8) { bf16x8 av[4];
; #pragma unroll
;                     for (int kt = 0; kt < 4; ++kt) av[kt] = *(const LAS bf16x8*)(KL + (16 * (4 * k8 + kt) + fr) * KSTR + (32 * k4 + 8 * fq) * 2);
; #pragma unroll
;                     for (int kt = 0; kt < 4; ++kt) s[4 * k8 + kt] = MFMA16(av[kt], qk, s[4 * k8 + kt]); } }
	v_mfma_f32_16x16x32_bf16 v[34:37], v[130:133], v[70:73], v[34:37]
	ds_read_b128 v[130:133], v208 offset:32768
	v_mfma_f32_16x16x32_bf16 v[38:41], v[134:137], v[70:73], v[38:41]
	ds_read_b128 v[134:137], v208 offset:36864
	v_mfma_f32_16x16x32_bf16 v[42:45], v[138:141], v[70:73], v[42:45]
	ds_read_b128 v[138:141], v208 offset:40960
	v_mfma_f32_16x16x32_bf16 v[46:49], v[142:145], v[70:73], v[46:49]
	ds_read_b128 v[142:145], v208 offset:45056
	v_mfma_f32_16x16x32_bf16 v[50:53], v[146:149], v[70:73], v[50:53]
	ds_read_b128 v[146:149], v208 offset:49152
	v_mfma_f32_16x16x32_bf16 v[54:57], v[150:153], v[70:73], v[54:57]
	ds_read_b128 v[150:153], v208 offset:53248
	v_mfma_f32_16x16x32_bf16 v[58:61], v[154:157], v[70:73], v[58:61]
	ds_read_b128 v[154:157], v208 offset:57344
	v_mfma_f32_16x16x32_bf16 v[62:65], v[158:161], v[70:73], v[62:65]
	ds_read_b128 v[158:161], v208 offset:61440
	s_waitcnt lgkmcnt(8)
	v_mfma_f32_16x16x32_bf16 v[2:5], v[98:101], v[74:77], v[2:5]
	ds_read_b128 v[98:101], v209 offset:0
	v_mfma_f32_16x16x32_bf16 v[6:9], v[102:105], v[74:77], v[6:9]
	ds_read_b128 v[102:105], v209 offset:4096
	v_mfma_f32_16x16x32_bf16 v[10:13], v[106:109], v[74:77], v[10:13]
	ds_read_b128 v[106:109], v209 offset:8192
	v_mfma_f32_16x16x32_bf16 v[14:17], v[110:113], v[74:77], v[14:17]
	ds_read_b128 v[110:113], v209 offset:12288
	v_mfma_f32_16x16x32_bf16 v[18:21], v[114:117], v[74:77], v[18:21]
	ds_read_b128 v[114:117], v209 offset:16384
	v_mfma_f32_16x16x32_bf16 v[22:25], v[118:121], v[74:77], v[22:25]
	ds_read_b128 v[118:121], v209 offset:20480
	v_mfma_f32_16x16x32_bf16 v[26:29], v[122:125], v[74:77], v[26:29]
	ds_read_b128 v[122:125], v209 offset:24576
	v_mfma_f32_16x16x32_bf16 v[30:33], v[126:129], v[74:77], v[30:33]
	ds_read_b128 v[126:129], v209 offset:28672
	s_waitcnt lgkmcnt(8)
	v_mfma_f32_16x16x32_bf16 v[34:37], v[130:133], v[74:77], v[34:37]
	ds_read_b128 v[130:133], v209 offset:32768
	v_mfma_f32_16x16x32_bf16 v[38:41], v[134:137], v[74:77], v[38:41]
	ds_read_b128 v[134:137], v209 offset:36864
	v_mfma_f32_16x16x32_bf16 v[42:45], v[138:141], v[74:77], v[42:45]
	ds_read_b128 v[138:141], v209 offset:40960
	v_mfma_f32_16x16x32_bf16 v[46:49], v[142:145], v[74:77], v[46:49]
	ds_read_b128 v[142:145], v209 offset:45056
	v_mfma_f32_16x16x32_bf16 v[50:53], v[146:149], v[74:77], v[50:53]
	ds_read_b128 v[146:149], v209 offset:49152
	v_mfma_f32_16x16x32_bf16 v[54:57], v[150:153], v[74:77], v[54:57]
	ds_read_b128 v[150:153], v209 offset:53248
	v_mfma_f32_16x16x32_bf16 v[58:61], v[154:157], v[74:77], v[58:61]
	ds_read_b128 v[154:157], v209 offset:57344
	v_mfma_f32_16x16x32_bf16 v[62:65], v[158:161], v[74:77], v[62:65]
	ds_read_b128 v[158:161], v209 offset:61440
	s_waitcnt lgkmcnt(8)
	v_mfma_f32_16x16x32_bf16 v[2:5], v[98:101], v[78:81], v[2:5]
	v_mfma_f32_16x16x32_bf16 v[6:9], v[102:105], v[78:81], v[6:9]
	v_mfma_f32_16x16x32_bf16 v[10:13], v[106:109], v[78:81], v[10:13]
	v_mfma_f32_16x16x32_bf16 v[14:17], v[110:113], v[78:81], v[14:17]
	v_mfma_f32_16x16x32_bf16 v[18:21], v[114:117], v[78:81], v[18:21]
	v_mfma_f32_16x16x32_bf16 v[22:25], v[118:121], v[78:81], v[22:25]
	v_mfma_f32_16x16x32_bf16 v[26:29], v[122:125], v[78:81], v[26:29]
	v_mfma_f32_16x16x32_bf16 v[30:33], v[126:129], v[78:81], v[30:33]
	s_waitcnt lgkmcnt(0)
	v_mfma_f32_16x16x32_bf16 v[34:37], v[130:133], v[78:81], v[34:37]
	v_mfma_f32_16x16x32_bf16 v[38:41], v[134:137], v[78:81], v[38:41]
	v_mfma_f32_16x16x32_bf16 v[42:45], v[138:141], v[78:81], v[42:45]
	v_mfma_f32_16x16x32_bf16 v[46:49], v[142:145], v[78:81], v[46:49]
	v_mfma_f32_16x16x32_bf16 v[50:53], v[146:149], v[78:81], v[50:53]
	v_mfma_f32_16x16x32_bf16 v[54:57], v[150:153], v[78:81], v[54:57]
	v_mfma_f32_16x16x32_bf16 v[58:61], v[154:157], v[78:81], v[58:61]
	v_mfma_f32_16x16x32_bf16 v[62:65], v[158:161], v[78:81], v[62:65]
	s_waitcnt vmcnt(0)
	s_barrier
	s_add_u32 s44, s42, 0
	s_addc_u32 s45, s43, 0
	v_lshrrev_b32_e32 v237, 5, v236
	v_add_u32_e32 v237, 0, v237
	v_and_b32_e32 v248, 31, v236
	v_xor_b32_e32 v248, v248, v237
	v_lshl_add_u32 v237, s16, 4, v237
	v_lshlrev_b32_e32 v237, 11, v237
	v_lshl_add_u32 v237, v248, 4, v237
	s_add_u32 m0, s49, 0
	s_nop 0
	global_load_lds_dwordx4 v237, s[44:45]
	v_lshrrev_b32_e32 v237, 5, v236
	v_add_u32_e32 v237, 2, v237
	v_and_b32_e32 v248, 31, v236
	v_xor_b32_e32 v248, v248, v237
	v_lshl_add_u32 v237, s16, 4, v237
	v_lshlrev_b32_e32 v237, 11, v237
	v_lshl_add_u32 v237, v248, 4, v237
	s_add_u32 m0, s49, 1024
	s_nop 0
	global_load_lds_dwordx4 v237, s[44:45]
	v_lshrrev_b32_e32 v237, 5, v236
	v_add_u32_e32 v237, 4, v237
	v_and_b32_e32 v248, 31, v236
	v_xor_b32_e32 v248, v248, v237
	v_lshl_add_u32 v237, s16, 4, v237
	v_lshlrev_b32_e32 v237, 11, v237
	v_lshl_add_u32 v237, v248, 4, v237
	s_add_u32 m0, s49, 2048
	s_nop 0
	global_load_lds_dwordx4 v237, s[44:45]
	v_lshrrev_b32_e32 v237, 5, v236
	v_add_u32_e32 v237, 6, v237
	v_and_b32_e32 v248, 31, v236
	v_xor_b32_e32 v248, v248, v237
	v_lshl_add_u32 v237, s16, 4, v237
	v_lshlrev_b32_e32 v237, 11, v237
	v_lshl_add_u32 v237, v248, 4, v237
	s_add_u32 m0, s49, 3072
	s_nop 0
	global_load_lds_dwordx4 v237, s[44:45]
	v_lshrrev_b32_e32 v237, 5, v236
	v_add_u32_e32 v237, 8, v237
	v_and_b32_e32 v248, 31, v236
	v_xor_b32_e32 v248, v248, v237
	v_lshl_add_u32 v237, s16, 4, v237
	v_lshlrev_b32_e32 v237, 11, v237
	v_lshl_add_u32 v237, v248, 4, v237
	s_add_u32 m0, s49, 4096
	s_nop 0
	global_load_lds_dwordx4 v237, s[44:45]
	v_lshrrev_b32_e32 v237, 5, v236
	v_add_u32_e32 v237, 10, v237
	v_and_b32_e32 v248, 31, v236
	v_xor_b32_e32 v248, v248, v237
	v_lshl_add_u32 v237, s16, 4, v237
	v_lshlrev_b32_e32 v237, 11, v237
	v_lshl_add_u32 v237, v248, 4, v237
	s_add_u32 m0, s49, 5120
	s_nop 0
	global_load_lds_dwordx4 v237, s[44:45]
	v_lshrrev_b32_e32 v237, 5, v236
	v_add_u32_e32 v237, 12, v237
	v_and_b32_e32 v248, 31, v236
	v_xor_b32_e32 v248, v248, v237
	v_lshl_add_u32 v237, s16, 4, v237
	v_lshlrev_b32_e32 v237, 11, v237
	v_lshl_add_u32 v237, v248, 4, v237
	s_add_u32 m0, s49, 6144
	s_nop 0
	global_load_lds_dwordx4 v237, s[44:45]
	v_lshrrev_b32_e32 v237, 5, v236
	v_add_u32_e32 v237, 14, v237
	v_and_b32_e32 v248, 31, v236
	v_xor_b32_e32 v248, v248, v237
	v_lshl_add_u32 v237, s16, 4, v237
	v_lshlrev_b32_e32 v237, 11, v237
	v_lshl_add_u32 v237, v248, 4, v237
	s_add_u32 m0, s49, 7168
	s_nop 0
	global_load_lds_dwordx4 v237, s[44:45]
	ds_read_b128 v[98:101], v212 offset:0
	ds_read_b128 v[102:105], v212 offset:4096
	ds_read_b128 v[106:109], v212 offset:8192
	ds_read_b128 v[110:113], v212 offset:12288
	ds_read_b128 v[114:117], v212 offset:16384
	ds_read_b128 v[118:121], v212 offset:20480
	ds_read_b128 v[122:125], v212 offset:24576
	ds_read_b128 v[126:129], v212 offset:28672
	ds_read_b128 v[130:133], v212 offset:32768
	ds_read_b128 v[134:137], v212 offset:36864
	ds_read_b128 v[138:141], v212 offset:40960
	ds_read_b128 v[142:145], v212 offset:45056
	ds_read_b128 v[146:149], v212 offset:49152
	ds_read_b128 v[150:153], v212 offset:53248
	ds_read_b128 v[154:157], v212 offset:57344
	ds_read_b128 v[158:161], v212 offset:61440
	s_waitcnt lgkmcnt(8)
; #define LAS __attribute__((address_space(3)))
; #define MFMA16(a, b, c) __builtin_amdgcn_mfma_f32_16x16x32_bf16((a), (b), (c), 0, 0, 0)
; DI void xattn_phase(LAS unsigned char* L, const bf16* Qx, const bf16* memK, const bf16* memVT, bf16* Ox, int G, int bid, int tid, unsigned long long& tsec) {
;     ...
;             for (int k4 = 0; k4 < 4; ++k4) { const bf16x8 qk = *(const bf16x8*)(Qx + tq * D + h * 256 + 128 * hh + 32 * k4 + 8 * fq);
; #pragma unroll
;                 for (int k8 = 0; k8 < 4; ++k8) { bf16x8 av[4];
; #pragma unroll
;                     for (int kt = 0; kt < 4; ++kt) av[kt] = *(const LAS bf16x8*)(KL + (16 * (4 * k8 + kt) + fr) * KSTR + (32 * k4 + 8 * fq) * 2);
; #pragma unroll
;                     for (int kt = 0; kt < 4; ++kt) s[4 * k8 + kt] = MFMA16(av[kt], qk, s[4 * k8 + kt]); } }
	v_mfma_f32_16x16x32_bf16 v[2:5], v[98:101], v[82:85], v[2:5]
	ds_read_b128 v[98:101], v213 offset:0
	v_mfma_f32_16x16x32_bf16 v[6:9], v[102:105], v[82:85], v[6:9]
	ds_read_b128 v[102:105], v213 offset:4096
	v_mfma_f32_16x16x32_bf16 v[10:13], v[106:109], v[82:85], v[10:13]
	ds_read_b128 v[106:109], v213 offset:8192
	v_mfma_f32_16x16x32_bf16 v[14:17], v[110:113], v[82:85], v[14:17]
	ds_read_b128 v[110:113], v213 offset:12288
	v_mfma_f32_16x16x32_bf16 v[18:21], v[114:117], v[82:85], v[18:21]
	ds_read_b128 v[114:117], v213 offset:16384
	v_mfma_f32_16x16x32_bf16 v[22:25], v[118:121], v[82:85], v[22:25]
	ds_read_b128 v[118:121], v213 offset:20480
	v_mfma_f32_16x16x32_bf16 v[26:29], v[122:125], v[82:85], v[26:29]
	ds_read_b128 v[122:125], v213 offset:24576
	v_mfma_f32_16x16x32_bf16 v[30:33], v[126:129], v[82:85], v[30:33]
	ds_read_b128 v[126:129], v213 offset:28672
	s_waitcnt lgkmcnt(8)
	v_mfma_f32_16x16x32_bf16 v[34:37], v[130:133], v[82:85], v[34:37]
	ds_read_b128 v[130:133], v213 offset:32768
	v_mfma_f32_16x16x32_bf16 v[38:41], v[134:137], v[82:85], v[38:41]
	ds_read_b128 v[134:137], v213 offset:36864
	v_mfma_f32_16x16x32_bf16 v[42:45], v[138:141], v[82:85], v[42:45]
	ds_read_b128 v[138:141], v213 offset:40960
	v_mfma_f32_16x16x32_bf16 v[46:49], v[142:145], v[82:85], v[46:49]
	ds_read_b128 v[142:145], v213 offset:45056
	v_mfma_f32_16x16x32_bf16 v[50:53], v[146:149], v[82:85], v[50:53]
	ds_read_b128 v[146:149], v213 offset:49152
	v_mfma_f32_16x16x32_bf16 v[54:57], v[150:153], v[82:85], v[54:57]
	ds_read_b128 v[150:153], v213 offset:53248
	v_mfma_f32_16x16x32_bf16 v[58:61], v[154:157], v[82:85], v[58:61]
	ds_read_b128 v[154:157], v213 offset:57344
	v_mfma_f32_16x16x32_bf16 v[62:65], v[158:161], v[82:85], v[62:65]
	ds_read_b128 v[158:161], v213 offset:61440
	s_waitcnt lgkmcnt(8)
	v_mfma_f32_16x16x32_bf16 v[2:5], v[98:101], v[86:89], v[2:5]
	ds_read_b128 v[98:101], v214 offset:0
	v_mfma_f32_16x16x32_bf16 v[6:9], v[102:105], v[86:89], v[6:9]
	ds_read_b128 v[102:105], v214 offset:4096
	v_mfma_f32_16x16x32_bf16 v[10:13], v[106:109], v[86:89], v[10:13]
	ds_read_b128 v[106:109], v214 offset:8192
	v_mfma_f32_16x16x32_bf16 v[14:17], v[110:113], v[86:89], v[14:17]
	ds_read_b128 v[110:113], v214 offset:12288
	v_mfma_f32_16x16x32_bf16 v[18:21], v[114:117], v[86:89], v[18:21]
	ds_read_b128 v[114:117], v214 offset:16384
	v_mfma_f32_16x16x32_bf16 v[22:25], v[118:121], v[86:89], v[22:25]
	ds_read_b128 v[118:121], v214 offset:20480
	v_mfma_f32_16x16x32_bf16 v[26:29], v[122:125], v[86:89], v[26:29]
	ds_read_b128 v[122:125], v214 offset:24576
	v_mfma_f32_16x16x32_bf16 v[30:33], v[126:129], v[86:89], v[30:33]
	ds_read_b128 v[126:129], v214 offset:28672
	s_waitcnt lgkmcnt(8)
	v_mfma_f32_16x16x32_bf16 v[34:37], v[130:133], v[86:89], v[34:37]
	ds_read_b128 v[130:133], v214 offset:32768
	v_mfma_f32_16x16x32_bf16 v[38:41], v[134:137], v[86:89], v[38:41]
	ds_read_b128 v[134:137], v214 offset:36864
	v_mfma_f32_16x16x32_bf16 v[42:45], v[138:141], v[86:89], v[42:45]
	ds_read_b128 v[138:141], v214 offset:40960
	v_mfma_f32_16x16x32_bf16 v[46:49], v[142:145], v[86:89], v[46:49]
	ds_read_b128 v[142:145], v214 offset:45056
	v_mfma_f32_16x16x32_bf16 v[50:53], v[146:149], v[86:89], v[50:53]
	ds_read_b128 v[146:149], v214 offset:49152
	v_mfma_f32_16x16x32_bf16 v[54:57], v[150:153], v[86:89], v[54:57]
	ds_read_b128 v[150:153], v214 offset:53248
	v_mfma_f32_16x16x32_bf16 v[58:61], v[154:157], v[86:89], v[58:61]
	ds_read_b128 v[154:157], v214 offset:57344
	v_mfma_f32_16x16x32_bf16 v[62:65], v[158:161], v[86:89], v[62:65]
	ds_read_b128 v[158:161], v214 offset:61440
	s_waitcnt lgkmcnt(8)
	v_mfma_f32_16x16x32_bf16 v[2:5], v[98:101], v[90:93], v[2:5]
	ds_read_b128 v[98:101], v215 offset:0
	v_mfma_f32_16x16x32_bf16 v[6:9], v[102:105], v[90:93], v[6:9]
	ds_read_b128 v[102:105], v215 offset:4096
	v_mfma_f32_16x16x32_bf16 v[10:13], v[106:109], v[90:93], v[10:13]
	ds_read_b128 v[106:109], v215 offset:8192
	v_mfma_f32_16x16x32_bf16 v[14:17], v[110:113], v[90:93], v[14:17]
	ds_read_b128 v[110:113], v215 offset:12288
	v_mfma_f32_16x16x32_bf16 v[18:21], v[114:117], v[90:93], v[18:21]
	ds_read_b128 v[114:117], v215 offset:16384
	v_mfma_f32_16x16x32_bf16 v[22:25], v[118:121], v[90:93], v[22:25]
	ds_read_b128 v[118:121], v215 offset:20480
	v_mfma_f32_16x16x32_bf16 v[26:29], v[122:125], v[90:93], v[26:29]
	ds_read_b128 v[122:125], v215 offset:24576
	v_mfma_f32_16x16x32_bf16 v[30:33], v[126:129], v[90:93], v[30:33]
	ds_read_b128 v[126:129], v215 offset:28672
	s_waitcnt lgkmcnt(8)
	v_mfma_f32_16x16x32_bf16 v[34:37], v[130:133], v[90:93], v[34:37]
	ds_read_b128 v[130:133], v215 offset:32768
	v_mfma_f32_16x16x32_bf16 v[38:41], v[134:137], v[90:93], v[38:41]
	ds_read_b128 v[134:137], v215 offset:36864
	v_mfma_f32_16x16x32_bf16 v[42:45], v[138:141], v[90:93], v[42:45]
	ds_read_b128 v[138:141], v215 offset:40960
	v_mfma_f32_16x16x32_bf16 v[46:49], v[142:145], v[90:93], v[46:49]
	ds_read_b128 v[142:145], v215 offset:45056
	v_mfma_f32_16x16x32_bf16 v[50:53], v[146:149], v[90:93], v[50:53]
	ds_read_b128 v[146:149], v215 offset:49152
	v_mfma_f32_16x16x32_bf16 v[54:57], v[150:153], v[90:93], v[54:57]
	ds_read_b128 v[150:153], v215 offset:53248
	v_mfma_f32_16x16x32_bf16 v[58:61], v[154:157], v[90:93], v[58:61]
	ds_read_b128 v[154:157], v215 offset:57344
	v_mfma_f32_16x16x32_bf16 v[62:65], v[158:161], v[90:93], v[62:65]
	ds_read_b128 v[158:161], v215 offset:61440
	s_waitcnt lgkmcnt(8)
; #define DSEC(k) do { if (PROBE_DSEC) { const unsigned long long tn_ = __builtin_amdgcn_s_memrealtime(); if (PROBE_DSEC == (k)) tsec += tn_ - tl_; tl_ = tn_; } } while (0)
; DI void xattn_phase(LAS unsigned char* L, const bf16* Qx, const bf16* memK, const bf16* memVT, bf16* Ox, int G, int bid, int tid, unsigned long long& tsec) {
;     ...
;         DSEC(12);
;         float mx = -INFINITY;
; #pragma unroll
;         for (int kt = 0; kt < 16; ++kt)
; #pragma unroll
;             for (int e = 0; e < 4; ++e) { const float v = s[kt][e] * 0.0625f; s[kt][e] = v; mx = fmaxf(mx, v); }
;         mx = fmaxf(mx, __shfl_xor(mx, 16)); mx = fmaxf(mx, __shfl_xor(mx, 32));
	v_mfma_f32_16x16x32_bf16 v[2:5], v[98:101], v[94:97], v[2:5]
	v_mfma_f32_16x16x32_bf16 v[6:9], v[102:105], v[94:97], v[6:9]
	v_mfma_f32_16x16x32_bf16 v[10:13], v[106:109], v[94:97], v[10:13]
	v_mfma_f32_16x16x32_bf16 v[14:17], v[110:113], v[94:97], v[14:17]
	v_mfma_f32_16x16x32_bf16 v[18:21], v[114:117], v[94:97], v[18:21]
	v_mfma_f32_16x16x32_bf16 v[22:25], v[118:121], v[94:97], v[22:25]
	v_mfma_f32_16x16x32_bf16 v[26:29], v[122:125], v[94:97], v[26:29]
	v_mfma_f32_16x16x32_bf16 v[30:33], v[126:129], v[94:97], v[30:33]
	s_waitcnt lgkmcnt(0)
	v_mfma_f32_16x16x32_bf16 v[34:37], v[130:133], v[94:97], v[34:37]
	v_mfma_f32_16x16x32_bf16 v[38:41], v[134:137], v[94:97], v[38:41]
	v_mfma_f32_16x16x32_bf16 v[42:45], v[138:141], v[94:97], v[42:45]
	v_mfma_f32_16x16x32_bf16 v[46:49], v[142:145], v[94:97], v[46:49]
	v_mfma_f32_16x16x32_bf16 v[50:53], v[146:149], v[94:97], v[50:53]
	v_mfma_f32_16x16x32_bf16 v[54:57], v[150:153], v[94:97], v[54:57]
	v_mfma_f32_16x16x32_bf16 v[58:61], v[154:157], v[94:97], v[58:61]
	v_mfma_f32_16x16x32_bf16 v[62:65], v[158:161], v[94:97], v[62:65]
	v_mul_f32_e32 v237, 0x3d800000, v2
	v_mul_f32_e32 v248, 0x3d800000, v3
	v_max_f32_e32 v249, v237, v248
	v_mul_f32_e32 v237, 0x3d800000, v4
	v_mul_f32_e32 v248, 0x3d800000, v5
	v_max3_f32 v249, v249, v237, v248
	v_mul_f32_e32 v237, 0x3d800000, v6
	v_mul_f32_e32 v248, 0x3d800000, v7
	v_max3_f32 v249, v249, v237, v248
	v_mul_f32_e32 v237, 0x3d800000, v8
	v_mul_f32_e32 v248, 0x3d800000, v9
	v_max3_f32 v249, v249, v237, v248
	v_mul_f32_e32 v237, 0x3d800000, v10
	v_mul_f32_e32 v248, 0x3d800000, v11
	v_max3_f32 v249, v249, v237, v248
	v_mul_f32_e32 v237, 0x3d800000, v12
	v_mul_f32_e32 v248, 0x3d800000, v13
	v_max3_f32 v249, v249, v237, v248
	v_mul_f32_e32 v237, 0x3d800000, v14
	v_mul_f32_e32 v248, 0x3d800000, v15
	v_max3_f32 v249, v249, v237, v248
	v_mul_f32_e32 v237, 0x3d800000, v16
	v_mul_f32_e32 v248, 0x3d800000, v17
	v_max3_f32 v249, v249, v237, v248
	v_mul_f32_e32 v237, 0x3d800000, v18
	v_mul_f32_e32 v248, 0x3d800000, v19
	v_max3_f32 v249, v249, v237, v248
	v_mul_f32_e32 v237, 0x3d800000, v20
	v_mul_f32_e32 v248, 0x3d800000, v21
	v_max3_f32 v249, v249, v237, v248
	v_mul_f32_e32 v237, 0x3d800000, v22
	v_mul_f32_e32 v248, 0x3d800000, v23
	v_max3_f32 v249, v249, v237, v248
	v_mul_f32_e32 v237, 0x3d800000, v24
	v_mul_f32_e32 v248, 0x3d800000, v25
	v_max3_f32 v249, v249, v237, v248
	v_mul_f32_e32 v237, 0x3d800000, v26
	v_mul_f32_e32 v248, 0x3d800000, v27
	v_max3_f32 v249, v249, v237, v248
	v_mul_f32_e32 v237, 0x3d800000, v28
	v_mul_f32_e32 v248, 0x3d800000, v29
	v_max3_f32 v249, v249, v237, v248
	v_mul_f32_e32 v237, 0x3d800000, v30
	v_mul_f32_e32 v248, 0x3d800000, v31
	v_max3_f32 v249, v249, v237, v248
	v_mul_f32_e32 v237, 0x3d800000, v32
	v_mul_f32_e32 v248, 0x3d800000, v33
	v_max3_f32 v249, v249, v237, v248
	v_mul_f32_e32 v237, 0x3d800000, v34
	v_mul_f32_e32 v248, 0x3d800000, v35
	v_max3_f32 v249, v249, v237, v248
	v_mul_f32_e32 v237, 0x3d800000, v36
	v_mul_f32_e32 v248, 0x3d800000, v37
	v_max3_f32 v249, v249, v237, v248
	v_mul_f32_e32 v237, 0x3d800000, v38
	v_mul_f32_e32 v248, 0x3d800000, v39
	v_max3_f32 v249, v249, v237, v248
	v_mul_f32_e32 v237, 0x3d800000, v40
	v_mul_f32_e32 v248, 0x3d800000, v41
	v_max3_f32 v249, v249, v237, v248
	v_mul_f32_e32 v237, 0x3d800000, v42
	v_mul_f32_e32 v248, 0x3d800000, v43
	v_max3_f32 v249, v249, v237, v248
	v_mul_f32_e32 v237, 0x3d800000, v44
	v_mul_f32_e32 v248, 0x3d800000, v45
	v_max3_f32 v249, v249, v237, v248
	v_mul_f32_e32 v237, 0x3d800000, v46
	v_mul_f32_e32 v248, 0x3d800000, v47
	v_max3_f32 v249, v249, v237, v248
	v_mul_f32_e32 v237, 0x3d800000, v48
	v_mul_f32_e32 v248, 0x3d800000, v49
	v_max3_f32 v249, v249, v237, v248
	v_mul_f32_e32 v237, 0x3d800000, v50
	v_mul_f32_e32 v248, 0x3d800000, v51
	v_max3_f32 v249, v249, v237, v248
	v_mul_f32_e32 v237, 0x3d800000, v52
	v_mul_f32_e32 v248, 0x3d800000, v53
	v_max3_f32 v249, v249, v237, v248
	v_mul_f32_e32 v237, 0x3d800000, v54
	v_mul_f32_e32 v248, 0x3d800000, v55
	v_max3_f32 v249, v249, v237, v248
	v_mul_f32_e32 v237, 0x3d800000, v56
	v_mul_f32_e32 v248, 0x3d800000, v57
	v_max3_f32 v249, v249, v237, v248
	v_mul_f32_e32 v237, 0x3d800000, v58
	v_mul_f32_e32 v248, 0x3d800000, v59
	v_max3_f32 v249, v249, v237, v248
	v_mul_f32_e32 v237, 0x3d800000, v60
	v_mul_f32_e32 v248, 0x3d800000, v61
	v_max3_f32 v249, v249, v237, v248
	v_mul_f32_e32 v237, 0x3d800000, v62
	v_mul_f32_e32 v248, 0x3d800000, v63
	v_max3_f32 v249, v249, v237, v248
	v_mul_f32_e32 v237, 0x3d800000, v64
	v_mul_f32_e32 v248, 0x3d800000, v65
	v_max3_f32 v249, v249, v237, v248
	ds_bpermute_b32 v237, v234, v249
	s_waitcnt lgkmcnt(0)
	v_max_f32_e32 v237, v237, v237
	v_max_f32_e32 v249, v249, v237
	ds_bpermute_b32 v237, v235, v249
	s_waitcnt lgkmcnt(0)
; DI void xattn_phase(LAS unsigned char* L, const bf16* Qx, const bf16* memK, const bf16* memVT, bf16* Ox, int G, int bid, int tid, unsigned long long& tsec) {
;     ...
;             for (int e = 0; e < 4; ++e) { const float v = s[kt][e] * 0.0625f; s[kt][e] = v; mx = fmaxf(mx, v); }
;         mx = fmaxf(mx, __shfl_xor(mx, 16)); mx = fmaxf(mx, __shfl_xor(mx, 32));
;         float den = 0.f;
; #pragma unroll
;         for (int kt = 0; kt < 16; ++kt)
; #pragma unroll
;             for (int e = 0; e < 4; ++e) { const float p = __expf(s[kt][e] - mx); s[kt][e] = p; den += p; }
	v_max_f32_e32 v237, v237, v237
	v_max_f32_e32 v249, v249, v237
	v_fma_f32 v2, v2, s48, -v249
	v_fma_f32 v3, v3, s48, -v249
	v_fma_f32 v4, v4, s48, -v249
	v_fma_f32 v5, v5, s48, -v249
	v_fma_f32 v6, v6, s48, -v249
	v_fma_f32 v7, v7, s48, -v249
	v_fma_f32 v8, v8, s48, -v249
	v_fma_f32 v9, v9, s48, -v249
	v_fma_f32 v10, v10, s48, -v249
	v_fma_f32 v11, v11, s48, -v249
	v_fma_f32 v12, v12, s48, -v249
	v_fma_f32 v13, v13, s48, -v249
	v_fma_f32 v14, v14, s48, -v249
	v_fma_f32 v15, v15, s48, -v249
	v_fma_f32 v16, v16, s48, -v249
	v_fma_f32 v17, v17, s48, -v249
	v_fma_f32 v18, v18, s48, -v249
	v_fma_f32 v19, v19, s48, -v249
	v_fma_f32 v20, v20, s48, -v249
	v_fma_f32 v21, v21, s48, -v249
	v_fma_f32 v22, v22, s48, -v249
	v_fma_f32 v23, v23, s48, -v249
	v_fma_f32 v24, v24, s48, -v249
	v_fma_f32 v25, v25, s48, -v249
	v_fma_f32 v26, v26, s48, -v249
	v_fma_f32 v27, v27, s48, -v249
	v_fma_f32 v28, v28, s48, -v249
	v_fma_f32 v29, v29, s48, -v249
	v_fma_f32 v30, v30, s48, -v249
	v_fma_f32 v31, v31, s48, -v249
	v_fma_f32 v32, v32, s48, -v249
	v_fma_f32 v33, v33, s48, -v249
	v_fma_f32 v34, v34, s48, -v249
	v_fma_f32 v35, v35, s48, -v249
	v_fma_f32 v36, v36, s48, -v249
	v_fma_f32 v37, v37, s48, -v249
	v_fma_f32 v38, v38, s48, -v249
	v_fma_f32 v39, v39, s48, -v249
	v_fma_f32 v40, v40, s48, -v249
	v_fma_f32 v41, v41, s48, -v249
	v_fma_f32 v42, v42, s48, -v249
	v_fma_f32 v43, v43, s48, -v249
	v_fma_f32 v44, v44, s48, -v249
	v_fma_f32 v45, v45, s48, -v249
	v_fma_f32 v46, v46, s48, -v249
	v_fma_f32 v47, v47, s48, -v249
	v_fma_f32 v48, v48, s48, -v249
	v_fma_f32 v49, v49, s48, -v249
	v_fma_f32 v50, v50, s48, -v249
	v_fma_f32 v51, v51, s48, -v249
	v_fma_f32 v52, v52, s48, -v249
	v_fma_f32 v53, v53, s48, -v249
	v_fma_f32 v54, v54, s48, -v249
	v_fma_f32 v55, v55, s48, -v249
	v_fma_f32 v56, v56, s48, -v249
	v_fma_f32 v57, v57, s48, -v249
	v_fma_f32 v58, v58, s48, -v249
	v_fma_f32 v59, v59, s48, -v249
	v_fma_f32 v60, v60, s48, -v249
	v_fma_f32 v61, v61, s48, -v249
	v_fma_f32 v62, v62, s48, -v249
	v_fma_f32 v63, v63, s48, -v249
	v_fma_f32 v64, v64, s48, -v249
	v_fma_f32 v65, v65, s48, -v249
	v_mul_f32_e32 v2, 0x3fb8aa3b, v2
	v_mul_f32_e32 v3, 0x3fb8aa3b, v3
	v_mul_f32_e32 v4, 0x3fb8aa3b, v4
	v_mul_f32_e32 v5, 0x3fb8aa3b, v5
	v_mul_f32_e32 v6, 0x3fb8aa3b, v6
	v_mul_f32_e32 v7, 0x3fb8aa3b, v7
	v_mul_f32_e32 v8, 0x3fb8aa3b, v8
	v_mul_f32_e32 v9, 0x3fb8aa3b, v9
	v_mul_f32_e32 v10, 0x3fb8aa3b, v10
	v_mul_f32_e32 v11, 0x3fb8aa3b, v11
	v_mul_f32_e32 v12, 0x3fb8aa3b, v12
	v_mul_f32_e32 v13, 0x3fb8aa3b, v13
	v_mul_f32_e32 v14, 0x3fb8aa3b, v14
	v_mul_f32_e32 v15, 0x3fb8aa3b, v15
	v_mul_f32_e32 v16, 0x3fb8aa3b, v16
	v_mul_f32_e32 v17, 0x3fb8aa3b, v17
	v_mul_f32_e32 v18, 0x3fb8aa3b, v18
	v_mul_f32_e32 v19, 0x3fb8aa3b, v19
	v_mul_f32_e32 v20, 0x3fb8aa3b, v20
	v_mul_f32_e32 v21, 0x3fb8aa3b, v21
	v_mul_f32_e32 v22, 0x3fb8aa3b, v22
	v_mul_f32_e32 v23, 0x3fb8aa3b, v23
	v_mul_f32_e32 v24, 0x3fb8aa3b, v24
	v_mul_f32_e32 v25, 0x3fb8aa3b, v25
	v_mul_f32_e32 v26, 0x3fb8aa3b, v26
	v_mul_f32_e32 v27, 0x3fb8aa3b, v27
	v_mul_f32_e32 v28, 0x3fb8aa3b, v28
	v_mul_f32_e32 v29, 0x3fb8aa3b, v29
	v_mul_f32_e32 v30, 0x3fb8aa3b, v30
	v_mul_f32_e32 v31, 0x3fb8aa3b, v31
	v_mul_f32_e32 v32, 0x3fb8aa3b, v32
	v_mul_f32_e32 v33, 0x3fb8aa3b, v33
	v_mul_f32_e32 v34, 0x3fb8aa3b, v34
	v_mul_f32_e32 v35, 0x3fb8aa3b, v35
	v_mul_f32_e32 v36, 0x3fb8aa3b, v36
	v_mul_f32_e32 v37, 0x3fb8aa3b, v37
	v_mul_f32_e32 v38, 0x3fb8aa3b, v38
	v_mul_f32_e32 v39, 0x3fb8aa3b, v39
	v_mul_f32_e32 v40, 0x3fb8aa3b, v40
	v_mul_f32_e32 v41, 0x3fb8aa3b, v41
	v_mul_f32_e32 v42, 0x3fb8aa3b, v42
	v_mul_f32_e32 v43, 0x3fb8aa3b, v43
	v_mul_f32_e32 v44, 0x3fb8aa3b, v44
	v_mul_f32_e32 v45, 0x3fb8aa3b, v45
	v_mul_f32_e32 v46, 0x3fb8aa3b, v46
	v_mul_f32_e32 v47, 0x3fb8aa3b, v47
	v_mul_f32_e32 v48, 0x3fb8aa3b, v48
	v_mul_f32_e32 v49, 0x3fb8aa3b, v49
	v_mul_f32_e32 v50, 0x3fb8aa3b, v50
	v_mul_f32_e32 v51, 0x3fb8aa3b, v51
	v_mul_f32_e32 v52, 0x3fb8aa3b, v52
	v_mul_f32_e32 v53, 0x3fb8aa3b, v53
	v_mul_f32_e32 v54, 0x3fb8aa3b, v54
	v_mul_f32_e32 v55, 0x3fb8aa3b, v55
	v_mul_f32_e32 v56, 0x3fb8aa3b, v56
	v_mul_f32_e32 v57, 0x3fb8aa3b, v57
	v_mul_f32_e32 v58, 0x3fb8aa3b, v58
	v_mul_f32_e32 v59, 0x3fb8aa3b, v59
	v_mul_f32_e32 v60, 0x3fb8aa3b, v60
	v_mul_f32_e32 v61, 0x3fb8aa3b, v61
	v_mul_f32_e32 v62, 0x3fb8aa3b, v62
	v_mul_f32_e32 v63, 0x3fb8aa3b, v63
	v_mul_f32_e32 v64, 0x3fb8aa3b, v64
	v_mul_f32_e32 v65, 0x3fb8aa3b, v65
	v_exp_f32_e32 v2, v2
	v_exp_f32_e32 v3, v3
	v_exp_f32_e32 v4, v4
	v_exp_f32_e32 v5, v5
	v_exp_f32_e32 v6, v6
	v_exp_f32_e32 v7, v7
	v_exp_f32_e32 v8, v8
	v_exp_f32_e32 v9, v9
	v_exp_f32_e32 v10, v10
	v_exp_f32_e32 v11, v11
	v_exp_f32_e32 v12, v12
	v_exp_f32_e32 v13, v13
	v_exp_f32_e32 v14, v14
	v_exp_f32_e32 v15, v15
	v_exp_f32_e32 v16, v16
	v_exp_f32_e32 v17, v17
	v_exp_f32_e32 v18, v18
	v_exp_f32_e32 v19, v19
	v_exp_f32_e32 v20, v20
	v_exp_f32_e32 v21, v21
	v_exp_f32_e32 v22, v22
	v_exp_f32_e32 v23, v23
	v_exp_f32_e32 v24, v24
	v_exp_f32_e32 v25, v25
	v_exp_f32_e32 v26, v26
	v_exp_f32_e32 v27, v27
	v_exp_f32_e32 v28, v28
	v_exp_f32_e32 v29, v29
	v_exp_f32_e32 v30, v30
	v_exp_f32_e32 v31, v31
	v_exp_f32_e32 v32, v32
	v_exp_f32_e32 v33, v33
	v_exp_f32_e32 v34, v34
	v_exp_f32_e32 v35, v35
	v_exp_f32_e32 v36, v36
	v_exp_f32_e32 v37, v37
	v_exp_f32_e32 v38, v38
	v_exp_f32_e32 v39, v39
	v_exp_f32_e32 v40, v40
	v_exp_f32_e32 v41, v41
	v_exp_f32_e32 v42, v42
	v_exp_f32_e32 v43, v43
	v_exp_f32_e32 v44, v44
	v_exp_f32_e32 v45, v45
	v_exp_f32_e32 v46, v46
	v_exp_f32_e32 v47, v47
	v_exp_f32_e32 v48, v48
	v_exp_f32_e32 v49, v49
	v_exp_f32_e32 v50, v50
	v_exp_f32_e32 v51, v51
	v_exp_f32_e32 v52, v52
	v_exp_f32_e32 v53, v53
	v_exp_f32_e32 v54, v54
; DI unsigned pk2(float lo, float hi) { const bf2_t r = __builtin_convertvector((f32x2_t){lo, hi}, bf2_t); return __builtin_bit_cast(unsigned, r); }
; #define DSEC(k) do { if (PROBE_DSEC) { const unsigned long long tn_ = __builtin_amdgcn_s_memrealtime(); if (PROBE_DSEC == (k)) tsec += tn_ - tl_; tl_ = tn_; } } while (0)
; #define XV_LOAD(R, b_, h_, hh_) do { _Pragma("unroll") for (int i = 0; i < 8; ++i) { const int p = tid + 512 * i, dhr = p >> 5, c = p & 31; R[i] = *(const u32x4*)(memVT + (size_t)((h_) * 256 + 128 * (hh_) + dhr) * MROWS + (b_) * NMEM + 8 * c); } } while (0)
; #define XV_WRITE(R) do { _Pragma("unroll") for (int i = 0; i < 8; ++i) { const int p = tid + 512 * i, dhr = p >> 5, c = p & 31; u32x2 lo, hi; lo.x = R[i].x; lo.y = R[i].y; hi.x = R[i].z; hi.y = R[i].w; \
;         *(LAS u32x2*)(VL + vt_off(dhr, 2 * c)) = lo; *(LAS u32x2*)(VL + vt_off(dhr, 2 * c + 1)) = hi; } } while (0)
; DI void xattn_phase(LAS unsigned char* L, const bf16* Qx, const bf16* memK, const bf16* memVT, bf16* Ox, int G, int bid, int tid, unsigned long long& tsec) {
;     ...
;         float den = 0.f;
; #pragma unroll
;         for (int kt = 0; kt < 16; ++kt)
; #pragma unroll
;             for (int e = 0; e < 4; ++e) { const float p = __expf(s[kt][e] - mx); s[kt][e] = p; den += p; }
;         den += __shfl_xor(den, 16); den += __shfl_xor(den, 32);
;         DSEC(13);
;         bf16x8 pf[8];
; #pragma unroll
;         for (int pp = 0; pp < 8; ++pp) { u32x4 pw; pw.x = pk2(s[2 * pp][0], s[2 * pp][1]); pw.y = pk2(s[2 * pp][2], s[2 * pp][3]); pw.z = pk2(s[2 * pp + 1][0], s[2 * pp + 1][1]); pw.w = pk2(s[2 * pp + 1][2], s[2 * pp + 1][3]); pf[pp] = mk8(pw); }
;         const float inv = __builtin_amdgcn_rcpf(den);
; #pragma unroll
;         for (int hh = 0; hh < 2; ++hh) {
;             if (hh == 1) { DSEC(14); __syncthreads(); XV_WRITE(rb); XV_LOAD(rb, bn, hn, 0); __syncthreads(); DSEC(15); }
	v_exp_f32_e32 v55, v55
	v_exp_f32_e32 v56, v56
	v_exp_f32_e32 v57, v57
	v_exp_f32_e32 v58, v58
	v_exp_f32_e32 v59, v59
	v_exp_f32_e32 v60, v60
	v_exp_f32_e32 v61, v61
	v_exp_f32_e32 v62, v62
	v_exp_f32_e32 v63, v63
	v_exp_f32_e32 v64, v64
	v_exp_f32_e32 v65, v65
	s_nop 0
	v_add_f32_e32 v237, v2, v3
	v_add_f32_e32 v237, v237, v4
	v_add_f32_e32 v237, v237, v5
	v_add_f32_e32 v237, v237, v6
	v_add_f32_e32 v237, v237, v7
	v_add_f32_e32 v237, v237, v8
	v_add_f32_e32 v237, v237, v9
	v_add_f32_e32 v237, v237, v10
	v_add_f32_e32 v237, v237, v11
	v_add_f32_e32 v237, v237, v12
	v_add_f32_e32 v237, v237, v13
	v_add_f32_e32 v237, v237, v14
	v_add_f32_e32 v237, v237, v15
	v_add_f32_e32 v237, v237, v16
	v_add_f32_e32 v237, v237, v17
	v_add_f32_e32 v237, v237, v18
	v_add_f32_e32 v237, v237, v19
	v_add_f32_e32 v237, v237, v20
	v_add_f32_e32 v237, v237, v21
	v_add_f32_e32 v237, v237, v22
	v_add_f32_e32 v237, v237, v23
	v_add_f32_e32 v237, v237, v24
	v_add_f32_e32 v237, v237, v25
	v_add_f32_e32 v237, v237, v26
	v_add_f32_e32 v237, v237, v27
	v_add_f32_e32 v237, v237, v28
	v_add_f32_e32 v237, v237, v29
	v_add_f32_e32 v237, v237, v30
	v_add_f32_e32 v237, v237, v31
	v_add_f32_e32 v237, v237, v32
	v_add_f32_e32 v237, v237, v33
	v_add_f32_e32 v237, v237, v34
	v_add_f32_e32 v237, v237, v35
	v_add_f32_e32 v237, v237, v36
	v_add_f32_e32 v237, v237, v37
	v_add_f32_e32 v237, v237, v38
	v_add_f32_e32 v237, v237, v39
	v_add_f32_e32 v237, v237, v40
	v_add_f32_e32 v237, v237, v41
	v_add_f32_e32 v237, v237, v42
	v_add_f32_e32 v237, v237, v43
	v_add_f32_e32 v237, v237, v44
	v_add_f32_e32 v237, v237, v45
	v_add_f32_e32 v237, v237, v46
	v_add_f32_e32 v237, v237, v47
	v_add_f32_e32 v237, v237, v48
	v_add_f32_e32 v237, v237, v49
	v_add_f32_e32 v237, v237, v50
	v_add_f32_e32 v237, v237, v51
	v_add_f32_e32 v237, v237, v52
	v_add_f32_e32 v237, v237, v53
	v_add_f32_e32 v237, v237, v54
	v_add_f32_e32 v237, v237, v55
	v_add_f32_e32 v237, v237, v56
	v_add_f32_e32 v237, v237, v57
	v_add_f32_e32 v237, v237, v58
	v_add_f32_e32 v237, v237, v59
	v_add_f32_e32 v237, v237, v60
	v_add_f32_e32 v237, v237, v61
	v_add_f32_e32 v237, v237, v62
	v_add_f32_e32 v237, v237, v63
	v_add_f32_e32 v237, v237, v64
	v_add_f32_e32 v237, v237, v65
	ds_bpermute_b32 v248, v234, v237
	s_waitcnt lgkmcnt(0)
	v_add_f32_e32 v237, v237, v248
	ds_bpermute_b32 v248, v235, v237
	s_waitcnt lgkmcnt(0)
	v_add_f32_e32 v237, v237, v248
	v_rcp_f32_e32 v0, v237
	v_cvt_pk_bf16_f32 v162, v2, v3
	v_cvt_pk_bf16_f32 v163, v4, v5
	v_cvt_pk_bf16_f32 v164, v6, v7
	v_cvt_pk_bf16_f32 v165, v8, v9
	v_cvt_pk_bf16_f32 v166, v10, v11
	v_cvt_pk_bf16_f32 v167, v12, v13
	v_cvt_pk_bf16_f32 v168, v14, v15
	v_cvt_pk_bf16_f32 v169, v16, v17
	v_cvt_pk_bf16_f32 v170, v18, v19
	v_cvt_pk_bf16_f32 v171, v20, v21
	v_cvt_pk_bf16_f32 v172, v22, v23
	v_cvt_pk_bf16_f32 v173, v24, v25
	v_cvt_pk_bf16_f32 v174, v26, v27
	v_cvt_pk_bf16_f32 v175, v28, v29
	v_cvt_pk_bf16_f32 v176, v30, v31
	v_cvt_pk_bf16_f32 v177, v32, v33
	v_cvt_pk_bf16_f32 v178, v34, v35
	v_cvt_pk_bf16_f32 v179, v36, v37
	v_cvt_pk_bf16_f32 v180, v38, v39
	v_cvt_pk_bf16_f32 v181, v40, v41
	v_cvt_pk_bf16_f32 v182, v42, v43
	v_cvt_pk_bf16_f32 v183, v44, v45
	v_cvt_pk_bf16_f32 v184, v46, v47
	v_cvt_pk_bf16_f32 v185, v48, v49
	v_cvt_pk_bf16_f32 v186, v50, v51
	v_cvt_pk_bf16_f32 v187, v52, v53
	v_cvt_pk_bf16_f32 v188, v54, v55
	v_cvt_pk_bf16_f32 v189, v56, v57
	v_cvt_pk_bf16_f32 v190, v58, v59
	v_cvt_pk_bf16_f32 v191, v60, v61
	v_cvt_pk_bf16_f32 v192, v62, v63
	v_cvt_pk_bf16_f32 v193, v64, v65
	s_waitcnt vmcnt(0)
	s_barrier
	s_add_u32 s44, s42, 262144
	s_addc_u32 s45, s43, 0
	v_lshrrev_b32_e32 v237, 5, v236
	v_add_u32_e32 v237, 0, v237
	v_and_b32_e32 v248, 31, v236
	v_xor_b32_e32 v248, v248, v237
	v_lshl_add_u32 v237, s16, 4, v237
	v_lshlrev_b32_e32 v237, 11, v237
	v_lshl_add_u32 v237, v248, 4, v237
	s_add_u32 m0, s49, 65536
	s_nop 0
	global_load_lds_dwordx4 v237, s[44:45]
	v_lshrrev_b32_e32 v237, 5, v236
	v_add_u32_e32 v237, 2, v237
	v_and_b32_e32 v248, 31, v236
	v_xor_b32_e32 v248, v248, v237
	v_lshl_add_u32 v237, s16, 4, v237
	v_lshlrev_b32_e32 v237, 11, v237
	v_lshl_add_u32 v237, v248, 4, v237
	s_add_u32 m0, s49, 66560
	s_nop 0
	global_load_lds_dwordx4 v237, s[44:45]
	v_lshrrev_b32_e32 v237, 5, v236
	v_add_u32_e32 v237, 4, v237
	v_and_b32_e32 v248, 31, v236
	v_xor_b32_e32 v248, v248, v237
	v_lshl_add_u32 v237, s16, 4, v237
	v_lshlrev_b32_e32 v237, 11, v237
	v_lshl_add_u32 v237, v248, 4, v237
	s_add_u32 m0, s49, 67584
	s_nop 0
	global_load_lds_dwordx4 v237, s[44:45]
	v_lshrrev_b32_e32 v237, 5, v236
	v_add_u32_e32 v237, 6, v237
	v_and_b32_e32 v248, 31, v236
	v_xor_b32_e32 v248, v248, v237
	v_lshl_add_u32 v237, s16, 4, v237
	v_lshlrev_b32_e32 v237, 11, v237
	v_lshl_add_u32 v237, v248, 4, v237
	s_add_u32 m0, s49, 68608
	s_nop 0
	global_load_lds_dwordx4 v237, s[44:45]
	v_lshrrev_b32_e32 v237, 5, v236
	v_add_u32_e32 v237, 8, v237
	v_and_b32_e32 v248, 31, v236
	v_xor_b32_e32 v248, v248, v237
	v_lshl_add_u32 v237, s16, 4, v237
	v_lshlrev_b32_e32 v237, 11, v237
	v_lshl_add_u32 v237, v248, 4, v237
	s_add_u32 m0, s49, 69632
	s_nop 0
	global_load_lds_dwordx4 v237, s[44:45]
	v_lshrrev_b32_e32 v237, 5, v236
	v_add_u32_e32 v237, 10, v237
	v_and_b32_e32 v248, 31, v236
	v_xor_b32_e32 v248, v248, v237
	v_lshl_add_u32 v237, s16, 4, v237
	v_lshlrev_b32_e32 v237, 11, v237
	v_lshl_add_u32 v237, v248, 4, v237
	s_add_u32 m0, s49, 70656
	s_nop 0
	global_load_lds_dwordx4 v237, s[44:45]
	v_lshrrev_b32_e32 v237, 5, v236
	v_add_u32_e32 v237, 12, v237
	v_and_b32_e32 v248, 31, v236
	v_xor_b32_e32 v248, v248, v237
	v_lshl_add_u32 v237, s16, 4, v237
	v_lshlrev_b32_e32 v237, 11, v237
	v_lshl_add_u32 v237, v248, 4, v237
; #define LAS __attribute__((address_space(3)))
; #define MFMA16(a, b, c) __builtin_amdgcn_mfma_f32_16x16x32_bf16((a), (b), (c), 0, 0, 0)
; DI void xattn_phase(LAS unsigned char* L, const bf16* Qx, const bf16* memK, const bf16* memVT, bf16* Ox, int G, int bid, int tid, unsigned long long& tsec) {
;     ...
;             const unsigned x0 = (unsigned)(fq ^ (fr >> 3));
;             const LAS unsigned char* vev = L + KL_BYTES + fr * VSTR + (x0 << 3); const LAS unsigned char* vod = L + KL_BYTES + fr * VSTR + ((x0 ^ 2u) << 3);
; #pragma unroll
;             for (int pp = 0; pp < 8; ++pp)
; #pragma unroll
;                 for (int d4 = 0; d4 < 2; ++d4) { bf16x8 vf[4];
; #pragma unroll
;                     for (int dq = 0; dq < 4; ++dq) { const int dt = 4 * d4 + dq; const LAS unsigned char* vb_ = ((dt & 1) ? vod : vev) + 16 * dt * VSTR + 64 * pp;
;                         const s16x4 lo = *(const LAS s16x4*)(vb_ + (((2 * dt) & 4) << 3)), hi = *(const LAS s16x4*)(vb_ + ((((2 * dt) & 4) ^ 4) << 3)); vf[dq] = __builtin_shufflevector(lo, hi, 0, 1, 2, 3, 4, 5, 6, 7); }
; #pragma unroll
;                     for (int dq = 0; dq < 4; ++dq) o[4 * d4 + dq] = MFMA16(vf[dq], pf[pp], o[4 * d4 + dq]);
;                 }
	s_add_u32 m0, s49, 71680
	s_nop 0
	global_load_lds_dwordx4 v237, s[44:45]
	v_lshrrev_b32_e32 v237, 5, v236
	v_add_u32_e32 v237, 14, v237
	v_and_b32_e32 v248, 31, v236
	v_xor_b32_e32 v248, v248, v237
	v_lshl_add_u32 v237, s16, 4, v237
	v_lshlrev_b32_e32 v237, 11, v237
	v_lshl_add_u32 v237, v248, 4, v237
	s_add_u32 m0, s49, 72704
	s_nop 0
	global_load_lds_dwordx4 v237, s[44:45]
	ds_read_b64 v[98:99], v216 offset:0
	ds_read_b64 v[100:101], v217 offset:0
	ds_read_b64 v[102:103], v216 offset:8192
	ds_read_b64 v[104:105], v217 offset:8192
	ds_read_b64 v[106:107], v216 offset:16384
	ds_read_b64 v[108:109], v217 offset:16384
	ds_read_b64 v[110:111], v216 offset:24576
	ds_read_b64 v[112:113], v217 offset:24576
	ds_read_b64 v[114:115], v216 offset:32768
	ds_read_b64 v[116:117], v217 offset:32768
	ds_read_b64 v[118:119], v216 offset:40960
	ds_read_b64 v[120:121], v217 offset:40960
	ds_read_b64 v[122:123], v216 offset:49152
	ds_read_b64 v[124:125], v217 offset:49152
	ds_read_b64 v[126:127], v216 offset:57344
	ds_read_b64 v[128:129], v217 offset:57344
	ds_read_b64 v[130:131], v218 offset:0
	ds_read_b64 v[132:133], v219 offset:0
	ds_read_b64 v[134:135], v218 offset:8192
	ds_read_b64 v[136:137], v219 offset:8192
	ds_read_b64 v[138:139], v218 offset:16384
	ds_read_b64 v[140:141], v219 offset:16384
	ds_read_b64 v[142:143], v218 offset:24576
	ds_read_b64 v[144:145], v219 offset:24576
	ds_read_b64 v[146:147], v218 offset:32768
	ds_read_b64 v[148:149], v219 offset:32768
	ds_read_b64 v[150:151], v218 offset:40960
	ds_read_b64 v[152:153], v219 offset:40960
	ds_read_b64 v[154:155], v218 offset:49152
	ds_read_b64 v[156:157], v219 offset:49152
	ds_read_b64 v[158:159], v218 offset:57344
	ds_read_b64 v[160:161], v219 offset:57344
	s_waitcnt lgkmcnt(15)
	v_mfma_f32_16x16x32_bf16 v[2:5], v[98:101], v[162:165], 0
	ds_read_b64 v[98:99], v220 offset:0
	ds_read_b64 v[100:101], v221 offset:0
	v_mfma_f32_16x16x32_bf16 v[6:9], v[102:105], v[162:165], 0
	ds_read_b64 v[102:103], v220 offset:8192
	ds_read_b64 v[104:105], v221 offset:8192
	v_mfma_f32_16x16x32_bf16 v[10:13], v[106:109], v[162:165], 0
	ds_read_b64 v[106:107], v220 offset:16384
	ds_read_b64 v[108:109], v221 offset:16384
	v_mfma_f32_16x16x32_bf16 v[14:17], v[110:113], v[162:165], 0
	ds_read_b64 v[110:111], v220 offset:24576
	ds_read_b64 v[112:113], v221 offset:24576
	v_mfma_f32_16x16x32_bf16 v[18:21], v[114:117], v[162:165], 0
	ds_read_b64 v[114:115], v220 offset:32768
	ds_read_b64 v[116:117], v221 offset:32768
	v_mfma_f32_16x16x32_bf16 v[22:25], v[118:121], v[162:165], 0
	ds_read_b64 v[118:119], v220 offset:40960
	ds_read_b64 v[120:121], v221 offset:40960
	v_mfma_f32_16x16x32_bf16 v[26:29], v[122:125], v[162:165], 0
	ds_read_b64 v[122:123], v220 offset:49152
	ds_read_b64 v[124:125], v221 offset:49152
	v_mfma_f32_16x16x32_bf16 v[30:33], v[126:129], v[162:165], 0
	ds_read_b64 v[126:127], v220 offset:57344
	ds_read_b64 v[128:129], v221 offset:57344
	s_waitcnt lgkmcnt(15)
	v_mfma_f32_16x16x32_bf16 v[2:5], v[130:133], v[166:169], v[2:5]
	ds_read_b64 v[130:131], v222 offset:0
	ds_read_b64 v[132:133], v223 offset:0
	v_mfma_f32_16x16x32_bf16 v[6:9], v[134:137], v[166:169], v[6:9]
	ds_read_b64 v[134:135], v222 offset:8192
	ds_read_b64 v[136:137], v223 offset:8192
	v_mfma_f32_16x16x32_bf16 v[10:13], v[138:141], v[166:169], v[10:13]
	ds_read_b64 v[138:139], v222 offset:16384
	ds_read_b64 v[140:141], v223 offset:16384
	v_mfma_f32_16x16x32_bf16 v[14:17], v[142:145], v[166:169], v[14:17]
	ds_read_b64 v[142:143], v222 offset:24576
	ds_read_b64 v[144:145], v223 offset:24576
	v_mfma_f32_16x16x32_bf16 v[18:21], v[146:149], v[166:169], v[18:21]
	ds_read_b64 v[146:147], v222 offset:32768
	ds_read_b64 v[148:149], v223 offset:32768
	v_mfma_f32_16x16x32_bf16 v[22:25], v[150:153], v[166:169], v[22:25]
	ds_read_b64 v[150:151], v222 offset:40960
	ds_read_b64 v[152:153], v223 offset:40960
	v_mfma_f32_16x16x32_bf16 v[26:29], v[154:157], v[166:169], v[26:29]
	ds_read_b64 v[154:155], v222 offset:49152
	ds_read_b64 v[156:157], v223 offset:49152
	v_mfma_f32_16x16x32_bf16 v[30:33], v[158:161], v[166:169], v[30:33]
	ds_read_b64 v[158:159], v222 offset:57344
	ds_read_b64 v[160:161], v223 offset:57344
	s_waitcnt lgkmcnt(15)
	v_mfma_f32_16x16x32_bf16 v[2:5], v[98:101], v[170:173], v[2:5]
	ds_read_b64 v[98:99], v216 offset:256
	ds_read_b64 v[100:101], v217 offset:256
	v_mfma_f32_16x16x32_bf16 v[6:9], v[102:105], v[170:173], v[6:9]
	ds_read_b64 v[102:103], v216 offset:8448
	ds_read_b64 v[104:105], v217 offset:8448
	v_mfma_f32_16x16x32_bf16 v[10:13], v[106:109], v[170:173], v[10:13]
	ds_read_b64 v[106:107], v216 offset:16640
	ds_read_b64 v[108:109], v217 offset:16640
	v_mfma_f32_16x16x32_bf16 v[14:17], v[110:113], v[170:173], v[14:17]
	ds_read_b64 v[110:111], v216 offset:24832
	ds_read_b64 v[112:113], v217 offset:24832
	v_mfma_f32_16x16x32_bf16 v[18:21], v[114:117], v[170:173], v[18:21]
	ds_read_b64 v[114:115], v216 offset:33024
	ds_read_b64 v[116:117], v217 offset:33024
	v_mfma_f32_16x16x32_bf16 v[22:25], v[118:121], v[170:173], v[22:25]
	ds_read_b64 v[118:119], v216 offset:41216
	ds_read_b64 v[120:121], v217 offset:41216
	v_mfma_f32_16x16x32_bf16 v[26:29], v[122:125], v[170:173], v[26:29]
	ds_read_b64 v[122:123], v216 offset:49408
	ds_read_b64 v[124:125], v217 offset:49408
	v_mfma_f32_16x16x32_bf16 v[30:33], v[126:129], v[170:173], v[30:33]
	ds_read_b64 v[126:127], v216 offset:57600
	ds_read_b64 v[128:129], v217 offset:57600
	s_waitcnt lgkmcnt(15)
; #define LAS __attribute__((address_space(3)))
; #define MFMA16(a, b, c) __builtin_amdgcn_mfma_f32_16x16x32_bf16((a), (b), (c), 0, 0, 0)
; DI void xattn_phase(LAS unsigned char* L, const bf16* Qx, const bf16* memK, const bf16* memVT, bf16* Ox, int G, int bid, int tid, unsigned long long& tsec) {
;     ...
;     for (int unit = bid; unit < 512; unit += G) {
;     ...
;             for (int pp = 0; pp < 8; ++pp)
; #pragma unroll
;                 for (int d4 = 0; d4 < 2; ++d4) { bf16x8 vf[4];
; #pragma unroll
;                     for (int dq = 0; dq < 4; ++dq) { const int dt = 4 * d4 + dq; const LAS unsigned char* vb_ = ((dt & 1) ? vod : vev) + 16 * dt * VSTR + 64 * pp;
;                         const s16x4 lo = *(const LAS s16x4*)(vb_ + (((2 * dt) & 4) << 3)), hi = *(const LAS s16x4*)(vb_ + ((((2 * dt) & 4) ^ 4) << 3)); vf[dq] = __builtin_shufflevector(lo, hi, 0, 1, 2, 3, 4, 5, 6, 7); }
; #pragma unroll
;                     for (int dq = 0; dq < 4; ++dq) o[4 * d4 + dq] = MFMA16(vf[dq], pf[pp], o[4 * d4 + dq]);
;                 }
	v_mfma_f32_16x16x32_bf16 v[2:5], v[130:133], v[174:177], v[2:5]
	ds_read_b64 v[130:131], v218 offset:256
	ds_read_b64 v[132:133], v219 offset:256
	v_mfma_f32_16x16x32_bf16 v[6:9], v[134:137], v[174:177], v[6:9]
	ds_read_b64 v[134:135], v218 offset:8448
	ds_read_b64 v[136:137], v219 offset:8448
	v_mfma_f32_16x16x32_bf16 v[10:13], v[138:141], v[174:177], v[10:13]
	ds_read_b64 v[138:139], v218 offset:16640
	ds_read_b64 v[140:141], v219 offset:16640
	v_mfma_f32_16x16x32_bf16 v[14:17], v[142:145], v[174:177], v[14:17]
	ds_read_b64 v[142:143], v218 offset:24832
	ds_read_b64 v[144:145], v219 offset:24832
	v_mfma_f32_16x16x32_bf16 v[18:21], v[146:149], v[174:177], v[18:21]
	ds_read_b64 v[146:147], v218 offset:33024
	ds_read_b64 v[148:149], v219 offset:33024
	v_mfma_f32_16x16x32_bf16 v[22:25], v[150:153], v[174:177], v[22:25]
	ds_read_b64 v[150:151], v218 offset:41216
	ds_read_b64 v[152:153], v219 offset:41216
	v_mfma_f32_16x16x32_bf16 v[26:29], v[154:157], v[174:177], v[26:29]
	ds_read_b64 v[154:155], v218 offset:49408
	ds_read_b64 v[156:157], v219 offset:49408
	v_mfma_f32_16x16x32_bf16 v[30:33], v[158:161], v[174:177], v[30:33]
	ds_read_b64 v[158:159], v218 offset:57600
	ds_read_b64 v[160:161], v219 offset:57600
	s_waitcnt lgkmcnt(15)
	v_mfma_f32_16x16x32_bf16 v[2:5], v[98:101], v[178:181], v[2:5]
	ds_read_b64 v[98:99], v220 offset:256
	ds_read_b64 v[100:101], v221 offset:256
	v_mfma_f32_16x16x32_bf16 v[6:9], v[102:105], v[178:181], v[6:9]
	ds_read_b64 v[102:103], v220 offset:8448
	ds_read_b64 v[104:105], v221 offset:8448
	v_mfma_f32_16x16x32_bf16 v[10:13], v[106:109], v[178:181], v[10:13]
	ds_read_b64 v[106:107], v220 offset:16640
	ds_read_b64 v[108:109], v221 offset:16640
	v_mfma_f32_16x16x32_bf16 v[14:17], v[110:113], v[178:181], v[14:17]
	ds_read_b64 v[110:111], v220 offset:24832
	ds_read_b64 v[112:113], v221 offset:24832
	v_mfma_f32_16x16x32_bf16 v[18:21], v[114:117], v[178:181], v[18:21]
	ds_read_b64 v[114:115], v220 offset:33024
	ds_read_b64 v[116:117], v221 offset:33024
	v_mfma_f32_16x16x32_bf16 v[22:25], v[118:121], v[178:181], v[22:25]
	ds_read_b64 v[118:119], v220 offset:41216
	ds_read_b64 v[120:121], v221 offset:41216
	v_mfma_f32_16x16x32_bf16 v[26:29], v[122:125], v[178:181], v[26:29]
	ds_read_b64 v[122:123], v220 offset:49408
	ds_read_b64 v[124:125], v221 offset:49408
	v_mfma_f32_16x16x32_bf16 v[30:33], v[126:129], v[178:181], v[30:33]
	ds_read_b64 v[126:127], v220 offset:57600
	ds_read_b64 v[128:129], v221 offset:57600
	s_waitcnt lgkmcnt(15)
	v_mfma_f32_16x16x32_bf16 v[2:5], v[130:133], v[182:185], v[2:5]
	ds_read_b64 v[130:131], v222 offset:256
	ds_read_b64 v[132:133], v223 offset:256
	v_mfma_f32_16x16x32_bf16 v[6:9], v[134:137], v[182:185], v[6:9]
	ds_read_b64 v[134:135], v222 offset:8448
	ds_read_b64 v[136:137], v223 offset:8448
	v_mfma_f32_16x16x32_bf16 v[10:13], v[138:141], v[182:185], v[10:13]
	ds_read_b64 v[138:139], v222 offset:16640
	ds_read_b64 v[140:141], v223 offset:16640
	v_mfma_f32_16x16x32_bf16 v[14:17], v[142:145], v[182:185], v[14:17]
	ds_read_b64 v[142:143], v222 offset:24832
	ds_read_b64 v[144:145], v223 offset:24832
	v_mfma_f32_16x16x32_bf16 v[18:21], v[146:149], v[182:185], v[18:21]
	ds_read_b64 v[146:147], v222 offset:33024
	ds_read_b64 v[148:149], v223 offset:33024
	v_mfma_f32_16x16x32_bf16 v[22:25], v[150:153], v[182:185], v[22:25]
	ds_read_b64 v[150:151], v222 offset:41216
	ds_read_b64 v[152:153], v223 offset:41216
	v_mfma_f32_16x16x32_bf16 v[26:29], v[154:157], v[182:185], v[26:29]
	ds_read_b64 v[154:155], v222 offset:49408
	ds_read_b64 v[156:157], v223 offset:49408
	v_mfma_f32_16x16x32_bf16 v[30:33], v[158:161], v[182:185], v[30:33]
	ds_read_b64 v[158:159], v222 offset:57600
	ds_read_b64 v[160:161], v223 offset:57600
	s_waitcnt lgkmcnt(15)
	v_mfma_f32_16x16x32_bf16 v[2:5], v[98:101], v[186:189], v[2:5]
	v_mfma_f32_16x16x32_bf16 v[6:9], v[102:105], v[186:189], v[6:9]
	v_mfma_f32_16x16x32_bf16 v[10:13], v[106:109], v[186:189], v[10:13]
	v_mfma_f32_16x16x32_bf16 v[14:17], v[110:113], v[186:189], v[14:17]
	v_mfma_f32_16x16x32_bf16 v[18:21], v[114:117], v[186:189], v[18:21]
	v_mfma_f32_16x16x32_bf16 v[22:25], v[118:121], v[186:189], v[22:25]
	v_mfma_f32_16x16x32_bf16 v[26:29], v[122:125], v[186:189], v[26:29]
	v_mfma_f32_16x16x32_bf16 v[30:33], v[126:129], v[186:189], v[30:33]
	s_waitcnt lgkmcnt(0)
	v_mfma_f32_16x16x32_bf16 v[2:5], v[130:133], v[190:193], v[2:5]
	v_mfma_f32_16x16x32_bf16 v[6:9], v[134:137], v[190:193], v[6:9]
	v_mfma_f32_16x16x32_bf16 v[10:13], v[138:141], v[190:193], v[10:13]
	v_mfma_f32_16x16x32_bf16 v[14:17], v[142:145], v[190:193], v[14:17]
	v_mfma_f32_16x16x32_bf16 v[18:21], v[146:149], v[190:193], v[18:21]
	v_mfma_f32_16x16x32_bf16 v[22:25], v[150:153], v[190:193], v[22:25]
	v_mfma_f32_16x16x32_bf16 v[26:29], v[154:157], v[190:193], v[26:29]
	v_mfma_f32_16x16x32_bf16 v[30:33], v[158:161], v[190:193], v[30:33]
	s_waitcnt vmcnt(0)
	s_barrier
	s_add_u32 s18, s17, s8
	s_cmp_lt_u32 s18, 0x200
	s_cbranch_scc0 .Lxa_last
; #define LAS __attribute__((address_space(3)))
; #define MFMA16(a, b, c) __builtin_amdgcn_mfma_f32_16x16x32_bf16((a), (b), (c), 0, 0, 0)
; #define XK_LOAD(R, b_, h_, hh_) do { _Pragma("unroll") for (int i = 0; i < 8; ++i) { const int p = tid + 512 * i, m = p >> 4, cb = p & 15; R[i] = *(const u32x4*)(memK + (size_t)((b_) * NMEM + m) * D + (h_) * 256 + 128 * (hh_) + 8 * cb); } } while (0)
; #define XK_WRITE(R) do { _Pragma("unroll") for (int i = 0; i < 8; ++i) { const int p = tid + 512 * i, m = p >> 4, cb = p & 15; *(LAS u32x4*)(KL + m * KSTR + 16 * cb) = R[i]; } } while (0)
; DI void xattn_phase(LAS unsigned char* L, const bf16* Qx, const bf16* memK, const bf16* memVT, bf16* Ox, int G, int bid, int tid, unsigned long long& tsec) {
;     ...
;     for (int unit = bid; unit < 512; unit += G) {
;         const int j = unit & 31, h = (unit >> 5) & 3, b = unit >> 7;
;         const int nun = unit + G < 512 ? unit + G : unit, hn = (nun >> 5) & 3, bn = nun >> 7;
;         asm volatile("" : "+v"(ra[0]), "+v"(ra[1]), "+v"(ra[2]), "+v"(ra[3]), "+v"(ra[4]), "+v"(ra[5]), "+v"(ra[6]), "+v"(ra[7]));
;         asm volatile("" : "+v"(rb[0]), "+v"(rb[1]), "+v"(rb[2]), "+v"(rb[3]), "+v"(rb[4]), "+v"(rb[5]), "+v"(rb[6]), "+v"(rb[7]));
;         const int tok0 = b * T + 128 * j; const size_t tq = (size_t)(tok0 + 16 * wid + fr);
;         f32x4 s[16];
; #pragma unroll
;         for (int kt = 0; kt < 16; ++kt) s[kt] = (f32x4){0.f, 0.f, 0.f, 0.f};
; #pragma unroll
;         for (int hh = 0; hh < 2; ++hh) {
;             __syncthreads();
;             XK_WRITE(ra);
;             if (hh == 0) { XV_WRITE(rb); XK_LOAD(ra, b, h, 1); XV_LOAD(rb, b, h, 1); }
;             else XK_LOAD(ra, bn, hn, 0);
;     ...
;             for (int pp = 0; pp < 8; ++pp)
; #pragma unroll
;                 for (int d4 = 0; d4 < 2; ++d4) { bf16x8 vf[4];
; #pragma unroll
;                     for (int dq = 0; dq < 4; ++dq) { const int dt = 4 * d4 + dq; const LAS unsigned char* vb_ = ((dt & 1) ? vod : vev) + 16 * dt * VSTR + 64 * pp;
;                         const s16x4 lo = *(const LAS s16x4*)(vb_ + (((2 * dt) & 4) << 3)), hi = *(const LAS s16x4*)(vb_ + ((((2 * dt) & 4) ^ 4) << 3)); vf[dq] = __builtin_shufflevector(lo, hi, 0, 1, 2, 3, 4, 5, 6, 7); }
; #pragma unroll
;                     for (int dq = 0; dq < 4; ++dq) o[4 * d4 + dq] = MFMA16(vf[dq], pf[pp], o[4 * d4 + dq]);
;                 }
	s_and_b32 s44, s18, 31
	s_bfe_u32 s45, s18, 0x20005
	s_lshr_b32 s46, s18, 7
	s_lshl_b32 s47, s46, 12
	s_lshl_b32 s44, s44, 7
	s_add_u32 s47, s47, s44
	s_lshl_b32 s47, s47, 11
	s_lshl_b32 s44, s45, 9
	s_add_u32 s47, s47, s44
	s_add_u32 s20, s0, s47
	s_addc_u32 s21, s1, 0
	s_lshl_b32 s47, s46, 19
	s_add_u32 s47, s47, s44
	s_add_u32 s24, s36, s47
	s_addc_u32 s25, s37, 0
	s_lshl_b32 s47, s45, 19
	s_lshl_b32 s44, s46, 9
	s_add_u32 s47, s47, s44
	s_add_u32 s42, s2, s47
	s_addc_u32 s43, s3, 0
	s_add_u32 s44, s24, 0
	s_addc_u32 s45, s25, 0
	s_add_u32 s46, s44, 0x8000
	s_addc_u32 s47, s45, 0
	s_add_u32 m0, s49, 0
	s_nop 0
	global_load_lds_dwordx4 v198, s[44:45]
	s_add_u32 m0, s49, 1024
	s_nop 0
	global_load_lds_dwordx4 v199, s[44:45]
	s_add_u32 m0, s49, 2048
	s_nop 0
	global_load_lds_dwordx4 v200, s[44:45]
	s_add_u32 m0, s49, 3072
	s_nop 0
	global_load_lds_dwordx4 v201, s[44:45]
	s_add_u32 m0, s49, 4096
	s_nop 0
	global_load_lds_dwordx4 v198, s[46:47]
	s_add_u32 m0, s49, 5120
	s_nop 0
	global_load_lds_dwordx4 v199, s[46:47]
	s_add_u32 m0, s49, 6144
	s_nop 0
	global_load_lds_dwordx4 v200, s[46:47]
	s_add_u32 m0, s49, 7168
	s_nop 0
	global_load_lds_dwordx4 v201, s[46:47]
	global_load_dwordx4 v[66:69], v232, s[20:21]
	global_load_dwordx4 v[70:73], v232, s[20:21] offset:64
	global_load_dwordx4 v[74:77], v232, s[20:21] offset:128
	global_load_dwordx4 v[78:81], v232, s[20:21] offset:192
	global_load_dwordx4 v[82:85], v232, s[20:21] offset:256
	global_load_dwordx4 v[86:89], v232, s[20:21] offset:320
	global_load_dwordx4 v[90:93], v232, s[20:21] offset:384
	global_load_dwordx4 v[94:97], v232, s[20:21] offset:448
	s_lshl_b32 s46, s16, 1
	s_add_u32 s46, s46, 0
	v_lshl_add_u32 v237, s46, 6, v236
	v_lshrrev_b32_e32 v248, 2, v237
	v_and_b32_e32 v237, 3, v237
	v_lshlrev_b32_e32 v237, 6, v237
	v_lshl_add_u32 v237, v248, 11, v237
	global_load_dword v249, v237, s[24:25] offset:256
	s_lshl_b32 s46, s16, 1
	s_add_u32 s46, s46, 1
	v_lshl_add_u32 v237, s46, 6, v236
	v_lshrrev_b32_e32 v248, 2, v237
	v_and_b32_e32 v237, 3, v237
	v_lshlrev_b32_e32 v237, 6, v237
	v_lshl_add_u32 v237, v248, 11, v237
	global_load_dword v249, v237, s[24:25] offset:256
	s_lshl_b32 s46, s16, 2
	s_add_u32 s46, s46, 0
	v_lshl_add_u32 v237, s46, 6, v236
	v_lshrrev_b32_e32 v248, 3, v237
	v_and_b32_e32 v237, 7, v237
	v_lshlrev_b32_e32 v237, 6, v237
	v_lshl_add_u32 v237, v248, 11, v237
	global_load_dword v249, v237, s[42:43]
	s_lshl_b32 s46, s16, 2
	s_add_u32 s46, s46, 1
	v_lshl_add_u32 v237, s46, 6, v236
	v_lshrrev_b32_e32 v248, 3, v237
	v_and_b32_e32 v237, 7, v237
	v_lshlrev_b32_e32 v237, 6, v237
	v_lshl_add_u32 v237, v248, 11, v237
	global_load_dword v249, v237, s[42:43]
	s_lshl_b32 s46, s16, 2
	s_add_u32 s46, s46, 2
	v_lshl_add_u32 v237, s46, 6, v236
	v_lshrrev_b32_e32 v248, 3, v237
	v_and_b32_e32 v237, 7, v237
	v_lshlrev_b32_e32 v237, 6, v237
	v_lshl_add_u32 v237, v248, 11, v237
	global_load_dword v249, v237, s[42:43]
	s_lshl_b32 s46, s16, 2
	s_add_u32 s46, s46, 3
	v_lshl_add_u32 v237, s46, 6, v236
	v_lshrrev_b32_e32 v248, 3, v237
	v_and_b32_e32 v237, 7, v237
	v_lshlrev_b32_e32 v237, 6, v237
	v_lshl_add_u32 v237, v248, 11, v237
	global_load_dword v249, v237, s[42:43]
	ds_read_b64 v[98:99], v224 offset:0
	ds_read_b64 v[100:101], v225 offset:0
	ds_read_b64 v[102:103], v224 offset:8192
	ds_read_b64 v[104:105], v225 offset:8192
	ds_read_b64 v[106:107], v224 offset:16384
	ds_read_b64 v[108:109], v225 offset:16384
	ds_read_b64 v[110:111], v224 offset:24576
	ds_read_b64 v[112:113], v225 offset:24576
	ds_read_b64 v[114:115], v224 offset:32768
	ds_read_b64 v[116:117], v225 offset:32768
	ds_read_b64 v[118:119], v224 offset:40960
	ds_read_b64 v[120:121], v225 offset:40960
	ds_read_b64 v[122:123], v224 offset:49152
	ds_read_b64 v[124:125], v225 offset:49152
	ds_read_b64 v[126:127], v224 offset:57344
	ds_read_b64 v[128:129], v225 offset:57344
	ds_read_b64 v[130:131], v226 offset:0
	ds_read_b64 v[132:133], v227 offset:0
	ds_read_b64 v[134:135], v226 offset:8192
	ds_read_b64 v[136:137], v227 offset:8192
	ds_read_b64 v[138:139], v226 offset:16384
	ds_read_b64 v[140:141], v227 offset:16384
	ds_read_b64 v[142:143], v226 offset:24576
	ds_read_b64 v[144:145], v227 offset:24576
	ds_read_b64 v[146:147], v226 offset:32768
	ds_read_b64 v[148:149], v227 offset:32768
	ds_read_b64 v[150:151], v226 offset:40960
	ds_read_b64 v[152:153], v227 offset:40960
	ds_read_b64 v[154:155], v226 offset:49152
	ds_read_b64 v[156:157], v227 offset:49152
	ds_read_b64 v[158:159], v226 offset:57344
	ds_read_b64 v[160:161], v227 offset:57344
	s_waitcnt lgkmcnt(15)
	v_mfma_f32_16x16x32_bf16 v[34:37], v[98:101], v[162:165], 0
	ds_read_b64 v[98:99], v228 offset:0
	ds_read_b64 v[100:101], v229 offset:0
	v_mfma_f32_16x16x32_bf16 v[38:41], v[102:105], v[162:165], 0
	ds_read_b64 v[102:103], v228 offset:8192
	ds_read_b64 v[104:105], v229 offset:8192
	v_mfma_f32_16x16x32_bf16 v[42:45], v[106:109], v[162:165], 0
	ds_read_b64 v[106:107], v228 offset:16384
	ds_read_b64 v[108:109], v229 offset:16384
	v_mfma_f32_16x16x32_bf16 v[46:49], v[110:113], v[162:165], 0
	ds_read_b64 v[110:111], v228 offset:24576
	ds_read_b64 v[112:113], v229 offset:24576
	v_mfma_f32_16x16x32_bf16 v[50:53], v[114:117], v[162:165], 0
	ds_read_b64 v[114:115], v228 offset:32768
	ds_read_b64 v[116:117], v229 offset:32768
	v_mfma_f32_16x16x32_bf16 v[54:57], v[118:121], v[162:165], 0
	ds_read_b64 v[118:119], v228 offset:40960
	ds_read_b64 v[120:121], v229 offset:40960
	v_mfma_f32_16x16x32_bf16 v[58:61], v[122:125], v[162:165], 0
	ds_read_b64 v[122:123], v228 offset:49152
	ds_read_b64 v[124:125], v229 offset:49152
	v_mfma_f32_16x16x32_bf16 v[62:65], v[126:129], v[162:165], 0
	ds_read_b64 v[126:127], v228 offset:57344
	ds_read_b64 v[128:129], v229 offset:57344
	s_waitcnt lgkmcnt(15)
; #define LAS __attribute__((address_space(3)))
; #define MFMA16(a, b, c) __builtin_amdgcn_mfma_f32_16x16x32_bf16((a), (b), (c), 0, 0, 0)
; DI void xattn_phase(LAS unsigned char* L, const bf16* Qx, const bf16* memK, const bf16* memVT, bf16* Ox, int G, int bid, int tid, unsigned long long& tsec) {
;     ...
;             for (int pp = 0; pp < 8; ++pp)
; #pragma unroll
;                 for (int d4 = 0; d4 < 2; ++d4) { bf16x8 vf[4];
; #pragma unroll
;                     for (int dq = 0; dq < 4; ++dq) { const int dt = 4 * d4 + dq; const LAS unsigned char* vb_ = ((dt & 1) ? vod : vev) + 16 * dt * VSTR + 64 * pp;
;                         const s16x4 lo = *(const LAS s16x4*)(vb_ + (((2 * dt) & 4) << 3)), hi = *(const LAS s16x4*)(vb_ + ((((2 * dt) & 4) ^ 4) << 3)); vf[dq] = __builtin_shufflevector(lo, hi, 0, 1, 2, 3, 4, 5, 6, 7); }
; #pragma unroll
;                     for (int dq = 0; dq < 4; ++dq) o[4 * d4 + dq] = MFMA16(vf[dq], pf[pp], o[4 * d4 + dq]);
;                 }
	v_mfma_f32_16x16x32_bf16 v[34:37], v[130:133], v[166:169], v[34:37]
	ds_read_b64 v[130:131], v230 offset:0
	ds_read_b64 v[132:133], v231 offset:0
	v_mfma_f32_16x16x32_bf16 v[38:41], v[134:137], v[166:169], v[38:41]
	ds_read_b64 v[134:135], v230 offset:8192
	ds_read_b64 v[136:137], v231 offset:8192
	v_mfma_f32_16x16x32_bf16 v[42:45], v[138:141], v[166:169], v[42:45]
	ds_read_b64 v[138:139], v230 offset:16384
	ds_read_b64 v[140:141], v231 offset:16384
	v_mfma_f32_16x16x32_bf16 v[46:49], v[142:145], v[166:169], v[46:49]
	ds_read_b64 v[142:143], v230 offset:24576
	ds_read_b64 v[144:145], v231 offset:24576
	v_mfma_f32_16x16x32_bf16 v[50:53], v[146:149], v[166:169], v[50:53]
	ds_read_b64 v[146:147], v230 offset:32768
	ds_read_b64 v[148:149], v231 offset:32768
	v_mfma_f32_16x16x32_bf16 v[54:57], v[150:153], v[166:169], v[54:57]
	ds_read_b64 v[150:151], v230 offset:40960
	ds_read_b64 v[152:153], v231 offset:40960
	v_mfma_f32_16x16x32_bf16 v[58:61], v[154:157], v[166:169], v[58:61]
	ds_read_b64 v[154:155], v230 offset:49152
	ds_read_b64 v[156:157], v231 offset:49152
	v_mfma_f32_16x16x32_bf16 v[62:65], v[158:161], v[166:169], v[62:65]
	ds_read_b64 v[158:159], v230 offset:57344
	ds_read_b64 v[160:161], v231 offset:57344
	s_waitcnt lgkmcnt(15)
	v_mfma_f32_16x16x32_bf16 v[34:37], v[98:101], v[170:173], v[34:37]
	ds_read_b64 v[98:99], v224 offset:256
	ds_read_b64 v[100:101], v225 offset:256
	v_mfma_f32_16x16x32_bf16 v[38:41], v[102:105], v[170:173], v[38:41]
	ds_read_b64 v[102:103], v224 offset:8448
	ds_read_b64 v[104:105], v225 offset:8448
	v_mfma_f32_16x16x32_bf16 v[42:45], v[106:109], v[170:173], v[42:45]
	ds_read_b64 v[106:107], v224 offset:16640
	ds_read_b64 v[108:109], v225 offset:16640
	v_mfma_f32_16x16x32_bf16 v[46:49], v[110:113], v[170:173], v[46:49]
	ds_read_b64 v[110:111], v224 offset:24832
	ds_read_b64 v[112:113], v225 offset:24832
	v_mfma_f32_16x16x32_bf16 v[50:53], v[114:117], v[170:173], v[50:53]
	ds_read_b64 v[114:115], v224 offset:33024
	ds_read_b64 v[116:117], v225 offset:33024
	v_mfma_f32_16x16x32_bf16 v[54:57], v[118:121], v[170:173], v[54:57]
	ds_read_b64 v[118:119], v224 offset:41216
	ds_read_b64 v[120:121], v225 offset:41216
	v_mfma_f32_16x16x32_bf16 v[58:61], v[122:125], v[170:173], v[58:61]
	ds_read_b64 v[122:123], v224 offset:49408
	ds_read_b64 v[124:125], v225 offset:49408
	v_mfma_f32_16x16x32_bf16 v[62:65], v[126:129], v[170:173], v[62:65]
	ds_read_b64 v[126:127], v224 offset:57600
	ds_read_b64 v[128:129], v225 offset:57600
	s_waitcnt lgkmcnt(15)
	v_mfma_f32_16x16x32_bf16 v[34:37], v[130:133], v[174:177], v[34:37]
	ds_read_b64 v[130:131], v226 offset:256
	ds_read_b64 v[132:133], v227 offset:256
	v_mfma_f32_16x16x32_bf16 v[38:41], v[134:137], v[174:177], v[38:41]
	ds_read_b64 v[134:135], v226 offset:8448
	ds_read_b64 v[136:137], v227 offset:8448
	v_mfma_f32_16x16x32_bf16 v[42:45], v[138:141], v[174:177], v[42:45]
	ds_read_b64 v[138:139], v226 offset:16640
	ds_read_b64 v[140:141], v227 offset:16640
	v_mfma_f32_16x16x32_bf16 v[46:49], v[142:145], v[174:177], v[46:49]
	ds_read_b64 v[142:143], v226 offset:24832
	ds_read_b64 v[144:145], v227 offset:24832
	v_mfma_f32_16x16x32_bf16 v[50:53], v[146:149], v[174:177], v[50:53]
	ds_read_b64 v[146:147], v226 offset:33024
	ds_read_b64 v[148:149], v227 offset:33024
	v_mfma_f32_16x16x32_bf16 v[54:57], v[150:153], v[174:177], v[54:57]
	ds_read_b64 v[150:151], v226 offset:41216
	ds_read_b64 v[152:153], v227 offset:41216
	v_mfma_f32_16x16x32_bf16 v[58:61], v[154:157], v[174:177], v[58:61]
	ds_read_b64 v[154:155], v226 offset:49408
	ds_read_b64 v[156:157], v227 offset:49408
	v_mfma_f32_16x16x32_bf16 v[62:65], v[158:161], v[174:177], v[62:65]
	ds_read_b64 v[158:159], v226 offset:57600
	ds_read_b64 v[160:161], v227 offset:57600
	s_waitcnt lgkmcnt(15)
	v_mfma_f32_16x16x32_bf16 v[34:37], v[98:101], v[178:181], v[34:37]
	ds_read_b64 v[98:99], v228 offset:256
	ds_read_b64 v[100:101], v229 offset:256
	v_mfma_f32_16x16x32_bf16 v[38:41], v[102:105], v[178:181], v[38:41]
	ds_read_b64 v[102:103], v228 offset:8448
	ds_read_b64 v[104:105], v229 offset:8448
	v_mfma_f32_16x16x32_bf16 v[42:45], v[106:109], v[178:181], v[42:45]
	ds_read_b64 v[106:107], v228 offset:16640
	ds_read_b64 v[108:109], v229 offset:16640
	v_mfma_f32_16x16x32_bf16 v[46:49], v[110:113], v[178:181], v[46:49]
	ds_read_b64 v[110:111], v228 offset:24832
	ds_read_b64 v[112:113], v229 offset:24832
	v_mfma_f32_16x16x32_bf16 v[50:53], v[114:117], v[178:181], v[50:53]
	ds_read_b64 v[114:115], v228 offset:33024
	ds_read_b64 v[116:117], v229 offset:33024
	v_mfma_f32_16x16x32_bf16 v[54:57], v[118:121], v[178:181], v[54:57]
	ds_read_b64 v[118:119], v228 offset:41216
	ds_read_b64 v[120:121], v229 offset:41216
	v_mfma_f32_16x16x32_bf16 v[58:61], v[122:125], v[178:181], v[58:61]
	ds_read_b64 v[122:123], v228 offset:49408
	ds_read_b64 v[124:125], v229 offset:49408
	v_mfma_f32_16x16x32_bf16 v[62:65], v[126:129], v[178:181], v[62:65]
	ds_read_b64 v[126:127], v228 offset:57600
	ds_read_b64 v[128:129], v229 offset:57600
	s_waitcnt lgkmcnt(15)
; DI unsigned pk2(float lo, float hi) { const bf2_t r = __builtin_convertvector((f32x2_t){lo, hi}, bf2_t); return __builtin_bit_cast(unsigned, r); }
; DI void xattn_phase(LAS unsigned char* L, const bf16* Qx, const bf16* memK, const bf16* memVT, bf16* Ox, int G, int bid, int tid, unsigned long long& tsec) {
;     ...
;     for (int unit = bid; unit < 512; unit += G) {
;         const int j = unit & 31, h = (unit >> 5) & 3, b = unit >> 7;
;         const int nun = unit + G < 512 ? unit + G : unit, hn = (nun >> 5) & 3, bn = nun >> 7;
;     ...
;             { bf16* op = Ox + tq * D + h * 256 + 128 * hh + 4 * fq;
; #pragma unroll
;               for (int dt = 0; dt < 8; ++dt) *(unsigned long long*)(op + 16 * dt) = (unsigned long long)pk2(o[dt][0] * inv, o[dt][1] * inv) | ((unsigned long long)pk2(o[dt][2] * inv, o[dt][3] * inv) << 32); }
	v_mfma_f32_16x16x32_bf16 v[34:37], v[130:133], v[182:185], v[34:37]
	ds_read_b64 v[130:131], v230 offset:256
	ds_read_b64 v[132:133], v231 offset:256
	v_mfma_f32_16x16x32_bf16 v[38:41], v[134:137], v[182:185], v[38:41]
	ds_read_b64 v[134:135], v230 offset:8448
	ds_read_b64 v[136:137], v231 offset:8448
	v_mfma_f32_16x16x32_bf16 v[42:45], v[138:141], v[182:185], v[42:45]
	ds_read_b64 v[138:139], v230 offset:16640
	ds_read_b64 v[140:141], v231 offset:16640
	v_mfma_f32_16x16x32_bf16 v[46:49], v[142:145], v[182:185], v[46:49]
	ds_read_b64 v[142:143], v230 offset:24832
	ds_read_b64 v[144:145], v231 offset:24832
	v_mfma_f32_16x16x32_bf16 v[50:53], v[146:149], v[182:185], v[50:53]
	ds_read_b64 v[146:147], v230 offset:33024
	ds_read_b64 v[148:149], v231 offset:33024
	v_mfma_f32_16x16x32_bf16 v[54:57], v[150:153], v[182:185], v[54:57]
	ds_read_b64 v[150:151], v230 offset:41216
	ds_read_b64 v[152:153], v231 offset:41216
	v_mfma_f32_16x16x32_bf16 v[58:61], v[154:157], v[182:185], v[58:61]
	ds_read_b64 v[154:155], v230 offset:49408
	ds_read_b64 v[156:157], v231 offset:49408
	v_mfma_f32_16x16x32_bf16 v[62:65], v[158:161], v[182:185], v[62:65]
	ds_read_b64 v[158:159], v230 offset:57600
	ds_read_b64 v[160:161], v231 offset:57600
	s_waitcnt lgkmcnt(15)
	v_mfma_f32_16x16x32_bf16 v[34:37], v[98:101], v[186:189], v[34:37]
	v_mfma_f32_16x16x32_bf16 v[38:41], v[102:105], v[186:189], v[38:41]
	v_mfma_f32_16x16x32_bf16 v[42:45], v[106:109], v[186:189], v[42:45]
	v_mfma_f32_16x16x32_bf16 v[46:49], v[110:113], v[186:189], v[46:49]
	v_mfma_f32_16x16x32_bf16 v[50:53], v[114:117], v[186:189], v[50:53]
	v_mfma_f32_16x16x32_bf16 v[54:57], v[118:121], v[186:189], v[54:57]
	v_mfma_f32_16x16x32_bf16 v[58:61], v[122:125], v[186:189], v[58:61]
	v_mfma_f32_16x16x32_bf16 v[62:65], v[126:129], v[186:189], v[62:65]
	s_waitcnt lgkmcnt(0)
	v_mfma_f32_16x16x32_bf16 v[34:37], v[130:133], v[190:193], v[34:37]
	v_mfma_f32_16x16x32_bf16 v[38:41], v[134:137], v[190:193], v[38:41]
	v_mfma_f32_16x16x32_bf16 v[42:45], v[138:141], v[190:193], v[42:45]
	v_mfma_f32_16x16x32_bf16 v[46:49], v[142:145], v[190:193], v[46:49]
	v_mfma_f32_16x16x32_bf16 v[50:53], v[146:149], v[190:193], v[50:53]
	v_mfma_f32_16x16x32_bf16 v[54:57], v[150:153], v[190:193], v[54:57]
	v_mfma_f32_16x16x32_bf16 v[58:61], v[154:157], v[190:193], v[58:61]
	v_mfma_f32_16x16x32_bf16 v[62:65], v[158:161], v[190:193], v[62:65]
	v_mul_f32_e32 v2, v0, v2
	v_mul_f32_e32 v3, v0, v3
	v_mul_f32_e32 v4, v0, v4
	v_mul_f32_e32 v5, v0, v5
	v_cvt_pk_bf16_f32 v2, v2, v3
	v_cvt_pk_bf16_f32 v3, v4, v5
	global_store_dwordx2 v233, v[2:3], s[22:23]
	v_mul_f32_e32 v6, v0, v6
	v_mul_f32_e32 v7, v0, v7
	v_mul_f32_e32 v8, v0, v8
	v_mul_f32_e32 v9, v0, v9
	v_cvt_pk_bf16_f32 v6, v6, v7
	v_cvt_pk_bf16_f32 v7, v8, v9
	global_store_dwordx2 v233, v[6:7], s[22:23] offset:32
	v_mul_f32_e32 v10, v0, v10
	v_mul_f32_e32 v11, v0, v11
	v_mul_f32_e32 v12, v0, v12
	v_mul_f32_e32 v13, v0, v13
	v_cvt_pk_bf16_f32 v10, v10, v11
	v_cvt_pk_bf16_f32 v11, v12, v13
	global_store_dwordx2 v233, v[10:11], s[22:23] offset:64
	v_mul_f32_e32 v14, v0, v14
	v_mul_f32_e32 v15, v0, v15
	v_mul_f32_e32 v16, v0, v16
	v_mul_f32_e32 v17, v0, v17
	v_cvt_pk_bf16_f32 v14, v14, v15
	v_cvt_pk_bf16_f32 v15, v16, v17
	global_store_dwordx2 v233, v[14:15], s[22:23] offset:96
	v_mul_f32_e32 v18, v0, v18
	v_mul_f32_e32 v19, v0, v19
	v_mul_f32_e32 v20, v0, v20
	v_mul_f32_e32 v21, v0, v21
	v_cvt_pk_bf16_f32 v18, v18, v19
	v_cvt_pk_bf16_f32 v19, v20, v21
	global_store_dwordx2 v233, v[18:19], s[22:23] offset:128
	v_mul_f32_e32 v22, v0, v22
	v_mul_f32_e32 v23, v0, v23
	v_mul_f32_e32 v24, v0, v24
	v_mul_f32_e32 v25, v0, v25
	v_cvt_pk_bf16_f32 v22, v22, v23
	v_cvt_pk_bf16_f32 v23, v24, v25
	global_store_dwordx2 v233, v[22:23], s[22:23] offset:160
	v_mul_f32_e32 v26, v0, v26
	v_mul_f32_e32 v27, v0, v27
	v_mul_f32_e32 v28, v0, v28
	v_mul_f32_e32 v29, v0, v29
	v_cvt_pk_bf16_f32 v26, v26, v27
	v_cvt_pk_bf16_f32 v27, v28, v29
	global_store_dwordx2 v233, v[26:27], s[22:23] offset:192
	v_mul_f32_e32 v30, v0, v30
	v_mul_f32_e32 v31, v0, v31
	v_mul_f32_e32 v32, v0, v32
	v_mul_f32_e32 v33, v0, v33
	v_cvt_pk_bf16_f32 v30, v30, v31
	v_cvt_pk_bf16_f32 v31, v32, v33
	global_store_dwordx2 v233, v[30:31], s[22:23] offset:224
	v_mul_f32_e32 v34, v0, v34
	v_mul_f32_e32 v35, v0, v35
	v_mul_f32_e32 v36, v0, v36
	v_mul_f32_e32 v37, v0, v37
	v_cvt_pk_bf16_f32 v34, v34, v35
	v_cvt_pk_bf16_f32 v35, v36, v37
	global_store_dwordx2 v233, v[34:35], s[22:23] offset:256
	v_mul_f32_e32 v38, v0, v38
	v_mul_f32_e32 v39, v0, v39
	v_mul_f32_e32 v40, v0, v40
	v_mul_f32_e32 v41, v0, v41
	v_cvt_pk_bf16_f32 v38, v38, v39
	v_cvt_pk_bf16_f32 v39, v40, v41
	global_store_dwordx2 v233, v[38:39], s[22:23] offset:288
	v_mul_f32_e32 v42, v0, v42
	v_mul_f32_e32 v43, v0, v43
	v_mul_f32_e32 v44, v0, v44
	v_mul_f32_e32 v45, v0, v45
	v_cvt_pk_bf16_f32 v42, v42, v43
	v_cvt_pk_bf16_f32 v43, v44, v45
	global_store_dwordx2 v233, v[42:43], s[22:23] offset:320
	v_mul_f32_e32 v46, v0, v46
	v_mul_f32_e32 v47, v0, v47
	v_mul_f32_e32 v48, v0, v48
	v_mul_f32_e32 v49, v0, v49
	v_cvt_pk_bf16_f32 v46, v46, v47
	v_cvt_pk_bf16_f32 v47, v48, v49
	global_store_dwordx2 v233, v[46:47], s[22:23] offset:352
	v_mul_f32_e32 v50, v0, v50
	v_mul_f32_e32 v51, v0, v51
	v_mul_f32_e32 v52, v0, v52
	v_mul_f32_e32 v53, v0, v53
	v_cvt_pk_bf16_f32 v50, v50, v51
	v_cvt_pk_bf16_f32 v51, v52, v53
	global_store_dwordx2 v233, v[50:51], s[22:23] offset:384
	v_mul_f32_e32 v54, v0, v54
	v_mul_f32_e32 v55, v0, v55
	v_mul_f32_e32 v56, v0, v56
	v_mul_f32_e32 v57, v0, v57
	v_cvt_pk_bf16_f32 v54, v54, v55
	v_cvt_pk_bf16_f32 v55, v56, v57
	global_store_dwordx2 v233, v[54:55], s[22:23] offset:416
	v_mul_f32_e32 v58, v0, v58
	v_mul_f32_e32 v59, v0, v59
	v_mul_f32_e32 v60, v0, v60
	v_mul_f32_e32 v61, v0, v61
	v_cvt_pk_bf16_f32 v58, v58, v59
	v_cvt_pk_bf16_f32 v59, v60, v61
	global_store_dwordx2 v233, v[58:59], s[22:23] offset:448
	v_mul_f32_e32 v62, v0, v62
	v_mul_f32_e32 v63, v0, v63
	v_mul_f32_e32 v64, v0, v64
	v_mul_f32_e32 v65, v0, v65
	v_cvt_pk_bf16_f32 v62, v62, v63
	v_cvt_pk_bf16_f32 v63, v64, v65
	global_store_dwordx2 v233, v[62:63], s[22:23] offset:480
	s_mov_b32 s17, s18
	s_and_b32 s44, s17, 31
	s_bfe_u32 s45, s17, 0x20005
	s_lshr_b32 s46, s17, 7
	s_lshl_b32 s47, s46, 12
	s_lshl_b32 s44, s44, 7
	s_add_u32 s47, s47, s44
	s_lshl_b32 s47, s47, 11
	s_lshl_b32 s44, s45, 9
	s_add_u32 s47, s47, s44
	s_add_u32 s22, s38, s47
	s_addc_u32 s23, s39, 0
	s_waitcnt vmcnt(16)
	s_barrier
	s_branch .Lxa_loop
; #define LAS __attribute__((address_space(3)))
; #define MFMA16(a, b, c) __builtin_amdgcn_mfma_f32_16x16x32_bf16((a), (b), (c), 0, 0, 0)
; DI void xattn_phase(LAS unsigned char* L, const bf16* Qx, const bf16* memK, const bf16* memVT, bf16* Ox, int G, int bid, int tid, unsigned long long& tsec) {
;     ...
;             for (int pp = 0; pp < 8; ++pp)
; #pragma unroll
;                 for (int d4 = 0; d4 < 2; ++d4) { bf16x8 vf[4];
; #pragma unroll
;                     for (int dq = 0; dq < 4; ++dq) { const int dt = 4 * d4 + dq; const LAS unsigned char* vb_ = ((dt & 1) ? vod : vev) + 16 * dt * VSTR + 64 * pp;
;                         const s16x4 lo = *(const LAS s16x4*)(vb_ + (((2 * dt) & 4) << 3)), hi = *(const LAS s16x4*)(vb_ + ((((2 * dt) & 4) ^ 4) << 3)); vf[dq] = __builtin_shufflevector(lo, hi, 0, 1, 2, 3, 4, 5, 6, 7); }
; #pragma unroll
;                     for (int dq = 0; dq < 4; ++dq) o[4 * d4 + dq] = MFMA16(vf[dq], pf[pp], o[4 * d4 + dq]);
;                 }
.Lxa_last:
	ds_read_b64 v[98:99], v224 offset:0
	ds_read_b64 v[100:101], v225 offset:0
	ds_read_b64 v[102:103], v224 offset:8192
	ds_read_b64 v[104:105], v225 offset:8192
	ds_read_b64 v[106:107], v224 offset:16384
	ds_read_b64 v[108:109], v225 offset:16384
	ds_read_b64 v[110:111], v224 offset:24576
	ds_read_b64 v[112:113], v225 offset:24576
	ds_read_b64 v[114:115], v224 offset:32768
	ds_read_b64 v[116:117], v225 offset:32768
	ds_read_b64 v[118:119], v224 offset:40960
	ds_read_b64 v[120:121], v225 offset:40960
	ds_read_b64 v[122:123], v224 offset:49152
	ds_read_b64 v[124:125], v225 offset:49152
	ds_read_b64 v[126:127], v224 offset:57344
	ds_read_b64 v[128:129], v225 offset:57344
	ds_read_b64 v[130:131], v226 offset:0
	ds_read_b64 v[132:133], v227 offset:0
	ds_read_b64 v[134:135], v226 offset:8192
	ds_read_b64 v[136:137], v227 offset:8192
	ds_read_b64 v[138:139], v226 offset:16384
	ds_read_b64 v[140:141], v227 offset:16384
	ds_read_b64 v[142:143], v226 offset:24576
	ds_read_b64 v[144:145], v227 offset:24576
	ds_read_b64 v[146:147], v226 offset:32768
	ds_read_b64 v[148:149], v227 offset:32768
	ds_read_b64 v[150:151], v226 offset:40960
	ds_read_b64 v[152:153], v227 offset:40960
	ds_read_b64 v[154:155], v226 offset:49152
	ds_read_b64 v[156:157], v227 offset:49152
	ds_read_b64 v[158:159], v226 offset:57344
	ds_read_b64 v[160:161], v227 offset:57344
	s_waitcnt lgkmcnt(15)
	v_mfma_f32_16x16x32_bf16 v[34:37], v[98:101], v[162:165], 0
	ds_read_b64 v[98:99], v228 offset:0
	ds_read_b64 v[100:101], v229 offset:0
	v_mfma_f32_16x16x32_bf16 v[38:41], v[102:105], v[162:165], 0
	ds_read_b64 v[102:103], v228 offset:8192
	ds_read_b64 v[104:105], v229 offset:8192
	v_mfma_f32_16x16x32_bf16 v[42:45], v[106:109], v[162:165], 0
	ds_read_b64 v[106:107], v228 offset:16384
	ds_read_b64 v[108:109], v229 offset:16384
	v_mfma_f32_16x16x32_bf16 v[46:49], v[110:113], v[162:165], 0
	ds_read_b64 v[110:111], v228 offset:24576
	ds_read_b64 v[112:113], v229 offset:24576
	v_mfma_f32_16x16x32_bf16 v[50:53], v[114:117], v[162:165], 0
	ds_read_b64 v[114:115], v228 offset:32768
	ds_read_b64 v[116:117], v229 offset:32768
	v_mfma_f32_16x16x32_bf16 v[54:57], v[118:121], v[162:165], 0
	ds_read_b64 v[118:119], v228 offset:40960
	ds_read_b64 v[120:121], v229 offset:40960
	v_mfma_f32_16x16x32_bf16 v[58:61], v[122:125], v[162:165], 0
	ds_read_b64 v[122:123], v228 offset:49152
	ds_read_b64 v[124:125], v229 offset:49152
	v_mfma_f32_16x16x32_bf16 v[62:65], v[126:129], v[162:165], 0
	ds_read_b64 v[126:127], v228 offset:57344
	ds_read_b64 v[128:129], v229 offset:57344
	s_waitcnt lgkmcnt(15)
	v_mfma_f32_16x16x32_bf16 v[34:37], v[130:133], v[166:169], v[34:37]
	ds_read_b64 v[130:131], v230 offset:0
	ds_read_b64 v[132:133], v231 offset:0
	v_mfma_f32_16x16x32_bf16 v[38:41], v[134:137], v[166:169], v[38:41]
	ds_read_b64 v[134:135], v230 offset:8192
	ds_read_b64 v[136:137], v231 offset:8192
	v_mfma_f32_16x16x32_bf16 v[42:45], v[138:141], v[166:169], v[42:45]
	ds_read_b64 v[138:139], v230 offset:16384
	ds_read_b64 v[140:141], v231 offset:16384
	v_mfma_f32_16x16x32_bf16 v[46:49], v[142:145], v[166:169], v[46:49]
	ds_read_b64 v[142:143], v230 offset:24576
	ds_read_b64 v[144:145], v231 offset:24576
	v_mfma_f32_16x16x32_bf16 v[50:53], v[146:149], v[166:169], v[50:53]
	ds_read_b64 v[146:147], v230 offset:32768
	ds_read_b64 v[148:149], v231 offset:32768
	v_mfma_f32_16x16x32_bf16 v[54:57], v[150:153], v[166:169], v[54:57]
	ds_read_b64 v[150:151], v230 offset:40960
	ds_read_b64 v[152:153], v231 offset:40960
	v_mfma_f32_16x16x32_bf16 v[58:61], v[154:157], v[166:169], v[58:61]
	ds_read_b64 v[154:155], v230 offset:49152
	ds_read_b64 v[156:157], v231 offset:49152
	v_mfma_f32_16x16x32_bf16 v[62:65], v[158:161], v[166:169], v[62:65]
	ds_read_b64 v[158:159], v230 offset:57344
	ds_read_b64 v[160:161], v231 offset:57344
	s_waitcnt lgkmcnt(15)
	v_mfma_f32_16x16x32_bf16 v[34:37], v[98:101], v[170:173], v[34:37]
	ds_read_b64 v[98:99], v224 offset:256
	ds_read_b64 v[100:101], v225 offset:256
	v_mfma_f32_16x16x32_bf16 v[38:41], v[102:105], v[170:173], v[38:41]
	ds_read_b64 v[102:103], v224 offset:8448
	ds_read_b64 v[104:105], v225 offset:8448
	v_mfma_f32_16x16x32_bf16 v[42:45], v[106:109], v[170:173], v[42:45]
	ds_read_b64 v[106:107], v224 offset:16640
	ds_read_b64 v[108:109], v225 offset:16640
	v_mfma_f32_16x16x32_bf16 v[46:49], v[110:113], v[170:173], v[46:49]
	ds_read_b64 v[110:111], v224 offset:24832
	ds_read_b64 v[112:113], v225 offset:24832
	v_mfma_f32_16x16x32_bf16 v[50:53], v[114:117], v[170:173], v[50:53]
	ds_read_b64 v[114:115], v224 offset:33024
	ds_read_b64 v[116:117], v225 offset:33024
	v_mfma_f32_16x16x32_bf16 v[54:57], v[118:121], v[170:173], v[54:57]
	ds_read_b64 v[118:119], v224 offset:41216
	ds_read_b64 v[120:121], v225 offset:41216
	v_mfma_f32_16x16x32_bf16 v[58:61], v[122:125], v[170:173], v[58:61]
	ds_read_b64 v[122:123], v224 offset:49408
	ds_read_b64 v[124:125], v225 offset:49408
	v_mfma_f32_16x16x32_bf16 v[62:65], v[126:129], v[170:173], v[62:65]
	ds_read_b64 v[126:127], v224 offset:57600
	ds_read_b64 v[128:129], v225 offset:57600
	s_waitcnt lgkmcnt(15)
; #define LAS __attribute__((address_space(3)))
; #define MFMA16(a, b, c) __builtin_amdgcn_mfma_f32_16x16x32_bf16((a), (b), (c), 0, 0, 0)
; DI void xattn_phase(LAS unsigned char* L, const bf16* Qx, const bf16* memK, const bf16* memVT, bf16* Ox, int G, int bid, int tid, unsigned long long& tsec) {
;     ...
;             for (int pp = 0; pp < 8; ++pp)
; #pragma unroll
;                 for (int d4 = 0; d4 < 2; ++d4) { bf16x8 vf[4];
; #pragma unroll
;                     for (int dq = 0; dq < 4; ++dq) { const int dt = 4 * d4 + dq; const LAS unsigned char* vb_ = ((dt & 1) ? vod : vev) + 16 * dt * VSTR + 64 * pp;
;                         const s16x4 lo = *(const LAS s16x4*)(vb_ + (((2 * dt) & 4) << 3)), hi = *(const LAS s16x4*)(vb_ + ((((2 * dt) & 4) ^ 4) << 3)); vf[dq] = __builtin_shufflevector(lo, hi, 0, 1, 2, 3, 4, 5, 6, 7); }
; #pragma unroll
;                     for (int dq = 0; dq < 4; ++dq) o[4 * d4 + dq] = MFMA16(vf[dq], pf[pp], o[4 * d4 + dq]);
;                 }
	v_mfma_f32_16x16x32_bf16 v[34:37], v[130:133], v[174:177], v[34:37]
	ds_read_b64 v[130:131], v226 offset:256
	ds_read_b64 v[132:133], v227 offset:256
	v_mfma_f32_16x16x32_bf16 v[38:41], v[134:137], v[174:177], v[38:41]
	ds_read_b64 v[134:135], v226 offset:8448
	ds_read_b64 v[136:137], v227 offset:8448
	v_mfma_f32_16x16x32_bf16 v[42:45], v[138:141], v[174:177], v[42:45]
	ds_read_b64 v[138:139], v226 offset:16640
	ds_read_b64 v[140:141], v227 offset:16640
	v_mfma_f32_16x16x32_bf16 v[46:49], v[142:145], v[174:177], v[46:49]
	ds_read_b64 v[142:143], v226 offset:24832
	ds_read_b64 v[144:145], v227 offset:24832
	v_mfma_f32_16x16x32_bf16 v[50:53], v[146:149], v[174:177], v[50:53]
	ds_read_b64 v[146:147], v226 offset:33024
	ds_read_b64 v[148:149], v227 offset:33024
	v_mfma_f32_16x16x32_bf16 v[54:57], v[150:153], v[174:177], v[54:57]
	ds_read_b64 v[150:151], v226 offset:41216
	ds_read_b64 v[152:153], v227 offset:41216
	v_mfma_f32_16x16x32_bf16 v[58:61], v[154:157], v[174:177], v[58:61]
	ds_read_b64 v[154:155], v226 offset:49408
	ds_read_b64 v[156:157], v227 offset:49408
	v_mfma_f32_16x16x32_bf16 v[62:65], v[158:161], v[174:177], v[62:65]
	ds_read_b64 v[158:159], v226 offset:57600
	ds_read_b64 v[160:161], v227 offset:57600
	s_waitcnt lgkmcnt(15)
	v_mfma_f32_16x16x32_bf16 v[34:37], v[98:101], v[178:181], v[34:37]
	ds_read_b64 v[98:99], v228 offset:256
	ds_read_b64 v[100:101], v229 offset:256
	v_mfma_f32_16x16x32_bf16 v[38:41], v[102:105], v[178:181], v[38:41]
	ds_read_b64 v[102:103], v228 offset:8448
	ds_read_b64 v[104:105], v229 offset:8448
	v_mfma_f32_16x16x32_bf16 v[42:45], v[106:109], v[178:181], v[42:45]
	ds_read_b64 v[106:107], v228 offset:16640
	ds_read_b64 v[108:109], v229 offset:16640
	v_mfma_f32_16x16x32_bf16 v[46:49], v[110:113], v[178:181], v[46:49]
	ds_read_b64 v[110:111], v228 offset:24832
	ds_read_b64 v[112:113], v229 offset:24832
	v_mfma_f32_16x16x32_bf16 v[50:53], v[114:117], v[178:181], v[50:53]
	ds_read_b64 v[114:115], v228 offset:33024
	ds_read_b64 v[116:117], v229 offset:33024
	v_mfma_f32_16x16x32_bf16 v[54:57], v[118:121], v[178:181], v[54:57]
	ds_read_b64 v[118:119], v228 offset:41216
	ds_read_b64 v[120:121], v229 offset:41216
	v_mfma_f32_16x16x32_bf16 v[58:61], v[122:125], v[178:181], v[58:61]
	ds_read_b64 v[122:123], v228 offset:49408
	ds_read_b64 v[124:125], v229 offset:49408
	v_mfma_f32_16x16x32_bf16 v[62:65], v[126:129], v[178:181], v[62:65]
	ds_read_b64 v[126:127], v228 offset:57600
	ds_read_b64 v[128:129], v229 offset:57600
	s_waitcnt lgkmcnt(15)
	v_mfma_f32_16x16x32_bf16 v[34:37], v[130:133], v[182:185], v[34:37]
	ds_read_b64 v[130:131], v230 offset:256
	ds_read_b64 v[132:133], v231 offset:256
	v_mfma_f32_16x16x32_bf16 v[38:41], v[134:137], v[182:185], v[38:41]
	ds_read_b64 v[134:135], v230 offset:8448
	ds_read_b64 v[136:137], v231 offset:8448
	v_mfma_f32_16x16x32_bf16 v[42:45], v[138:141], v[182:185], v[42:45]
	ds_read_b64 v[138:139], v230 offset:16640
	ds_read_b64 v[140:141], v231 offset:16640
	v_mfma_f32_16x16x32_bf16 v[46:49], v[142:145], v[182:185], v[46:49]
	ds_read_b64 v[142:143], v230 offset:24832
	ds_read_b64 v[144:145], v231 offset:24832
	v_mfma_f32_16x16x32_bf16 v[50:53], v[146:149], v[182:185], v[50:53]
	ds_read_b64 v[146:147], v230 offset:33024
	ds_read_b64 v[148:149], v231 offset:33024
	v_mfma_f32_16x16x32_bf16 v[54:57], v[150:153], v[182:185], v[54:57]
	ds_read_b64 v[150:151], v230 offset:41216
	ds_read_b64 v[152:153], v231 offset:41216
	v_mfma_f32_16x16x32_bf16 v[58:61], v[154:157], v[182:185], v[58:61]
	ds_read_b64 v[154:155], v230 offset:49408
	ds_read_b64 v[156:157], v231 offset:49408
	v_mfma_f32_16x16x32_bf16 v[62:65], v[158:161], v[182:185], v[62:65]
	ds_read_b64 v[158:159], v230 offset:57600
	ds_read_b64 v[160:161], v231 offset:57600
	s_waitcnt lgkmcnt(15)
	v_mfma_f32_16x16x32_bf16 v[34:37], v[98:101], v[186:189], v[34:37]
	v_mfma_f32_16x16x32_bf16 v[38:41], v[102:105], v[186:189], v[38:41]
	v_mfma_f32_16x16x32_bf16 v[42:45], v[106:109], v[186:189], v[42:45]
	v_mfma_f32_16x16x32_bf16 v[46:49], v[110:113], v[186:189], v[46:49]
	v_mfma_f32_16x16x32_bf16 v[50:53], v[114:117], v[186:189], v[50:53]
	v_mfma_f32_16x16x32_bf16 v[54:57], v[118:121], v[186:189], v[54:57]
	v_mfma_f32_16x16x32_bf16 v[58:61], v[122:125], v[186:189], v[58:61]
	v_mfma_f32_16x16x32_bf16 v[62:65], v[126:129], v[186:189], v[62:65]
	s_waitcnt lgkmcnt(0)
; DI unsigned pk2(float lo, float hi) { const bf2_t r = __builtin_convertvector((f32x2_t){lo, hi}, bf2_t); return __builtin_bit_cast(unsigned, r); }
; DI void xattn_phase(LAS unsigned char* L, const bf16* Qx, const bf16* memK, const bf16* memVT, bf16* Ox, int G, int bid, int tid, unsigned long long& tsec) {
;     ...
;             { bf16* op = Ox + tq * D + h * 256 + 128 * hh + 4 * fq;
; #pragma unroll
;               for (int dt = 0; dt < 8; ++dt) *(unsigned long long*)(op + 16 * dt) = (unsigned long long)pk2(o[dt][0] * inv, o[dt][1] * inv) | ((unsigned long long)pk2(o[dt][2] * inv, o[dt][3] * inv) << 32); }
	v_mfma_f32_16x16x32_bf16 v[34:37], v[130:133], v[190:193], v[34:37]
	v_mfma_f32_16x16x32_bf16 v[38:41], v[134:137], v[190:193], v[38:41]
	v_mfma_f32_16x16x32_bf16 v[42:45], v[138:141], v[190:193], v[42:45]
	v_mfma_f32_16x16x32_bf16 v[46:49], v[142:145], v[190:193], v[46:49]
	v_mfma_f32_16x16x32_bf16 v[50:53], v[146:149], v[190:193], v[50:53]
	v_mfma_f32_16x16x32_bf16 v[54:57], v[150:153], v[190:193], v[54:57]
	v_mfma_f32_16x16x32_bf16 v[58:61], v[154:157], v[190:193], v[58:61]
	v_mfma_f32_16x16x32_bf16 v[62:65], v[158:161], v[190:193], v[62:65]
	v_mul_f32_e32 v2, v0, v2
	v_mul_f32_e32 v3, v0, v3
	v_mul_f32_e32 v4, v0, v4
	v_mul_f32_e32 v5, v0, v5
	v_cvt_pk_bf16_f32 v2, v2, v3
	v_cvt_pk_bf16_f32 v3, v4, v5
	global_store_dwordx2 v233, v[2:3], s[22:23]
	v_mul_f32_e32 v6, v0, v6
	v_mul_f32_e32 v7, v0, v7
	v_mul_f32_e32 v8, v0, v8
	v_mul_f32_e32 v9, v0, v9
	v_cvt_pk_bf16_f32 v6, v6, v7
	v_cvt_pk_bf16_f32 v7, v8, v9
	global_store_dwordx2 v233, v[6:7], s[22:23] offset:32
	v_mul_f32_e32 v10, v0, v10
	v_mul_f32_e32 v11, v0, v11
	v_mul_f32_e32 v12, v0, v12
	v_mul_f32_e32 v13, v0, v13
	v_cvt_pk_bf16_f32 v10, v10, v11
	v_cvt_pk_bf16_f32 v11, v12, v13
	global_store_dwordx2 v233, v[10:11], s[22:23] offset:64
	v_mul_f32_e32 v14, v0, v14
	v_mul_f32_e32 v15, v0, v15
	v_mul_f32_e32 v16, v0, v16
	v_mul_f32_e32 v17, v0, v17
	v_cvt_pk_bf16_f32 v14, v14, v15
	v_cvt_pk_bf16_f32 v15, v16, v17
	global_store_dwordx2 v233, v[14:15], s[22:23] offset:96
	v_mul_f32_e32 v18, v0, v18
	v_mul_f32_e32 v19, v0, v19
	v_mul_f32_e32 v20, v0, v20
	v_mul_f32_e32 v21, v0, v21
	v_cvt_pk_bf16_f32 v18, v18, v19
	v_cvt_pk_bf16_f32 v19, v20, v21
	global_store_dwordx2 v233, v[18:19], s[22:23] offset:128
	v_mul_f32_e32 v22, v0, v22
	v_mul_f32_e32 v23, v0, v23
	v_mul_f32_e32 v24, v0, v24
	v_mul_f32_e32 v25, v0, v25
	v_cvt_pk_bf16_f32 v22, v22, v23
	v_cvt_pk_bf16_f32 v23, v24, v25
	global_store_dwordx2 v233, v[22:23], s[22:23] offset:160
	v_mul_f32_e32 v26, v0, v26
	v_mul_f32_e32 v27, v0, v27
	v_mul_f32_e32 v28, v0, v28
	v_mul_f32_e32 v29, v0, v29
	v_cvt_pk_bf16_f32 v26, v26, v27
	v_cvt_pk_bf16_f32 v27, v28, v29
	global_store_dwordx2 v233, v[26:27], s[22:23] offset:192
	v_mul_f32_e32 v30, v0, v30
	v_mul_f32_e32 v31, v0, v31
	v_mul_f32_e32 v32, v0, v32
	v_mul_f32_e32 v33, v0, v33
	v_cvt_pk_bf16_f32 v30, v30, v31
	v_cvt_pk_bf16_f32 v31, v32, v33
	global_store_dwordx2 v233, v[30:31], s[22:23] offset:224
	v_mul_f32_e32 v34, v0, v34
	v_mul_f32_e32 v35, v0, v35
	v_mul_f32_e32 v36, v0, v36
	v_mul_f32_e32 v37, v0, v37
	v_cvt_pk_bf16_f32 v34, v34, v35
	v_cvt_pk_bf16_f32 v35, v36, v37
	global_store_dwordx2 v233, v[34:35], s[22:23] offset:256
	v_mul_f32_e32 v38, v0, v38
	v_mul_f32_e32 v39, v0, v39
	v_mul_f32_e32 v40, v0, v40
	v_mul_f32_e32 v41, v0, v41
	v_cvt_pk_bf16_f32 v38, v38, v39
	v_cvt_pk_bf16_f32 v39, v40, v41
	global_store_dwordx2 v233, v[38:39], s[22:23] offset:288
	v_mul_f32_e32 v42, v0, v42
	v_mul_f32_e32 v43, v0, v43
	v_mul_f32_e32 v44, v0, v44
	v_mul_f32_e32 v45, v0, v45
	v_cvt_pk_bf16_f32 v42, v42, v43
	v_cvt_pk_bf16_f32 v43, v44, v45
	global_store_dwordx2 v233, v[42:43], s[22:23] offset:320
	v_mul_f32_e32 v46, v0, v46
	v_mul_f32_e32 v47, v0, v47
	v_mul_f32_e32 v48, v0, v48
	v_mul_f32_e32 v49, v0, v49
	v_cvt_pk_bf16_f32 v46, v46, v47
	v_cvt_pk_bf16_f32 v47, v48, v49
	global_store_dwordx2 v233, v[46:47], s[22:23] offset:352
	v_mul_f32_e32 v50, v0, v50
	v_mul_f32_e32 v51, v0, v51
	v_mul_f32_e32 v52, v0, v52
	v_mul_f32_e32 v53, v0, v53
	v_cvt_pk_bf16_f32 v50, v50, v51
	v_cvt_pk_bf16_f32 v51, v52, v53
	global_store_dwordx2 v233, v[50:51], s[22:23] offset:384
	v_mul_f32_e32 v54, v0, v54
	v_mul_f32_e32 v55, v0, v55
	v_mul_f32_e32 v56, v0, v56
	v_mul_f32_e32 v57, v0, v57
	v_cvt_pk_bf16_f32 v54, v54, v55
	v_cvt_pk_bf16_f32 v55, v56, v57
	global_store_dwordx2 v233, v[54:55], s[22:23] offset:416
	v_mul_f32_e32 v58, v0, v58
	v_mul_f32_e32 v59, v0, v59
	v_mul_f32_e32 v60, v0, v60
	v_mul_f32_e32 v61, v0, v61
	v_cvt_pk_bf16_f32 v58, v58, v59
	v_cvt_pk_bf16_f32 v59, v60, v61
	global_store_dwordx2 v233, v[58:59], s[22:23] offset:448
	v_mul_f32_e32 v62, v0, v62
	v_mul_f32_e32 v63, v0, v63
	v_mul_f32_e32 v64, v0, v64
	v_mul_f32_e32 v65, v0, v65
	v_cvt_pk_bf16_f32 v62, v62, v63
	v_cvt_pk_bf16_f32 v63, v64, v65
	global_store_dwordx2 v233, v[62:63], s[22:23] offset:480
